# nt (non-temporal) hint on once-read streaming loads: P5 states, P1 x rows, P7 residual x, P9 residual X1
# speedup vs baseline: 1.0057x; 1.0046x over previous
; __global__ void __launch_bounds__(NT, 2) fwd_kernel(Args args) {
;     ...
;         _Pragma("unroll 1") for (int grp = 0; grp < 3; ++grp) {
;             if (grp == 2 && wave >= 4) break;
;             const int nr = (grp < 2) ? 4 : 1, toff = (grp < 2) ? 0 : 2048;
;             f32x4 v[4][4];
; #pragma unroll
;             for (int q = 0; q < 4; ++q) { if (q < nr) { const float* src = (grp < 2) ? x + (size_t)(64 * bl + 8 * wave + 4 * grp + q) * D : ctx + (size_t)(4 * bl + wave) * D;
; #pragma unroll
;                 for (int j = 0; j < 4; ++j) v[q][j] = *(const f32x4*)(src + 4 * (lane + 64 * j)); } }
.LBB0_106:
	s_add_i32 s0, s20, 3
	s_ashr_i32 s1, s0, 31
	s_lshl_b64 s[0:1], s[0:1], 12
	v_lshl_add_u64 v[62:63], v[86:87], 0, s[0:1]
	global_load_dwordx4 v[46:49], v[62:63], off nt
	global_load_dwordx4 v[54:57], v[62:63], off offset:1024 nt
	global_load_dwordx4 v[58:61], v[62:63], off offset:2048 nt
	s_nop 0
	global_load_dwordx4 v[62:65], v[62:63], off offset:3072 nt
	s_mov_b32 s3, 0
	s_mov_b64 s[0:1], s[20:21]

; __global__ void __launch_bounds__(NT, 2) fwd_kernel(Args args) {
;     ...
;             for (int q = 0; q < 4; ++q) { if (q < nr) { const float* src = (grp < 2) ? x + (size_t)(64 * bl + 8 * wave + 4 * grp + q) * D : ctx + (size_t)(4 * bl + wave) * D;
; #pragma unroll
;                 for (int j = 0; j < 4; ++j) v[q][j] = *(const f32x4*)(src + 4 * (lane + 64 * j)); } }
.LBB0_109:
	s_add_i32 s0, s20, 1
	s_ashr_i32 s1, s0, 31
	s_lshl_b64 s[0:1], s[0:1], 12
	v_lshl_add_u64 v[38:39], v[86:87], 0, s[0:1]
	global_load_dwordx4 v[18:21], v[38:39], off nt
	global_load_dwordx4 v[22:25], v[38:39], off offset:1024 nt
	global_load_dwordx4 v[30:33], v[38:39], off offset:2048 nt
	s_nop 0
	global_load_dwordx4 v[38:41], v[38:39], off offset:3072 nt
	s_and_b64 vcc, exec, s[4:5]
	s_cbranch_vccnz .LBB0_105
.LBB0_110:
	s_add_i32 s0, s20, 2
	s_ashr_i32 s1, s0, 31
	s_lshl_b64 s[0:1], s[0:1], 12
	v_lshl_add_u64 v[50:51], v[86:87], 0, s[0:1]
	global_load_dwordx4 v[26:29], v[50:51], off nt
	global_load_dwordx4 v[34:37], v[50:51], off offset:1024 nt
	global_load_dwordx4 v[42:45], v[50:51], off offset:2048 nt
	s_nop 0
	global_load_dwordx4 v[50:53], v[50:51], off offset:3072 nt
	s_movk_i32 s3, 0x800
	s_and_b64 vcc, exec, s[4:5]
	s_mov_b64 s[0:1], s[14:15]
	s_cbranch_vccz .LBB0_106
	s_branch .LBB0_107

; __global__ void __launch_bounds__(NT, 2) fwd_kernel(Args args) {
;     ...
;             const int g2 = gt - 65536, chain = g2 >> 10, b = chain >> 4, hh = (chain >> 1) & 7, d = chain & 1, e = 4 * (g2 & 1023);
;             float s0 = 0.f, s1 = 0.f, s2 = 0.f, s3 = 0.f;
;             _Pragma("unroll 1") for (int st = 0; st < 72; st += 8) {
;                 v2u loc[8]; float dec[8]; bf16* ad[8];
; #pragma unroll
;                 for (int u = 0; u < 8; ++u) { const int ch = chain_chunk(b, d, (st + u < 68) ? st + u : 67); ad[u] = STS + (size_t)((ch * 8 + hh) * 2 + d) * 4096 + e; loc[u] = *(const v2u*)ad[u];
;                     dec[u] = DECS[(size_t)(ch * 2 + d) * 8 + hh]; }
.LBB0_678:
	s_cmp_lg_u32 s3, -2
	s_cselect_b64 s[0:1], -1, 0
	s_cmp_eq_u32 s3, -2
	s_cselect_b64 vcc, -1, 0
	s_add_i32 s12, s8, -4
	s_waitcnt vmcnt(2)
	v_mov_b32_e32 v2, s9
	v_mov_b32_e32 v12, s12
	v_cndmask_b32_e64 v2, v2, v12, s[4:5]
	v_add_u32_e32 v2, v2, v13
	v_cndmask_b32_e32 v2, v2, v21, vcc
	v_lshl_or_b32 v14, v2, 4, v55
	v_ashrrev_i32_e32 v15, 31, v14
	v_lshlrev_b64 v[14:15], 13, v[14:15]
	s_add_i32 s12, s8, -3
	s_add_i32 s13, s9, -1
	v_lshl_add_u64 v[16:17], v[4:5], 0, v[14:15]
	v_lshl_or_b32 v14, v2, 1, v1
	v_mov_b32_e32 v2, s13
	v_mov_b32_e32 v12, s12
	v_cndmask_b32_e64 v2, v2, v12, s[4:5]
	v_ashrrev_i32_e32 v15, 31, v14
	v_add_u32_e32 v2, v2, v13
	v_lshlrev_b64 v[14:15], 5, v[14:15]
	v_cndmask_b32_e32 v2, v2, v27, vcc
	v_lshl_add_u64 v[18:19], v[6:7], 0, v[14:15]
	v_lshl_or_b32 v14, v2, 4, v55
	v_lshl_or_b32 v22, v2, 1, v1
	v_ashrrev_i32_e32 v15, 31, v14
	v_ashrrev_i32_e32 v23, 31, v22
	v_lshlrev_b64 v[14:15], 13, v[14:15]
	v_lshlrev_b64 v[22:23], 5, v[22:23]
	v_lshl_add_u64 v[14:15], v[4:5], 0, v[14:15]
	v_lshl_add_u64 v[22:23], v[6:7], 0, v[22:23]
	global_load_dwordx2 v[28:29], v[16:17], off nt
	global_load_dword v26, v[18:19], off
	global_load_dword v12, v[22:23], off
	s_nop 0
	global_load_dwordx2 v[18:19], v[14:15], off nt
	s_and_b64 vcc, exec, vcc
	v_mov_b32_e32 v2, v47
	s_cbranch_vccnz .LBB0_680
	s_add_i32 s12, s9, -2
	v_mov_b32_e32 v2, s12
	v_mov_b32_e32 v20, s3
	v_cndmask_b32_e64 v2, v2, v20, s[4:5]
	v_add_u32_e32 v2, v2, v13
.LBB0_680:
	v_lshl_or_b32 v22, v2, 4, v55
	v_ashrrev_i32_e32 v23, 31, v22
	v_lshl_or_b32 v24, v2, 1, v1
	v_lshlrev_b64 v[22:23], 13, v[22:23]
	v_ashrrev_i32_e32 v25, 31, v24
	v_lshl_add_u64 v[22:23], v[4:5], 0, v[22:23]
	v_lshlrev_b64 v[24:25], 5, v[24:25]
	v_lshl_add_u64 v[30:31], v[6:7], 0, v[24:25]
	global_load_dwordx2 v[24:25], v[22:23], off nt
	global_load_dword v20, v[30:31], off
	s_andn2_b64 vcc, exec, s[0:1]
	v_mov_b32_e32 v2, v51
	s_cbranch_vccnz .LBB0_682
	s_add_i32 s0, s3, 1
	s_add_i32 s1, s9, -3
	v_mov_b32_e32 v2, s1
	v_mov_b32_e32 v30, s0
	v_cndmask_b32_e64 v2, v2, v30, s[4:5]
	v_add_u32_e32 v2, v2, v13
; __device__ __forceinline__ unsigned pk2(float lo, float hi) { const f32x2cv v = {lo, hi}; const bf16x2cv b = __builtin_convertvector(v, bf16x2cv); return __builtin_bit_cast(unsigned, b); }
; __global__ void __launch_bounds__(NT, 2) fwd_kernel(Args args) {
;     ...
;             _Pragma("unroll 1") for (int st = 0; st < 72; st += 8) {
;                 v2u loc[8]; float dec[8]; bf16* ad[8];
; #pragma unroll
;                 for (int u = 0; u < 8; ++u) { const int ch = chain_chunk(b, d, (st + u < 68) ? st + u : 67); ad[u] = STS + (size_t)((ch * 8 + hh) * 2 + d) * 4096 + e; loc[u] = *(const v2u*)ad[u];
;                     dec[u] = DECS[(size_t)(ch * 2 + d) * 8 + hh]; }
; #pragma unroll
;                 for (int u = 0; u < 8; ++u) { if (st + u >= 68) break; v2u o; o.x = pk2(s0, s1); o.y = pk2(s2, s3); *(v2u*)ad[u] = o;
;                     s0 = s0 * dec[u] + bflo(loc[u].x); s1 = s1 * dec[u] + bfhi(loc[u].x); s2 = s2 * dec[u] + bflo(loc[u].y); s3 = s3 * dec[u] + bfhi(loc[u].y); }
;             }
.LBB0_682:
	v_lshl_or_b32 v32, v2, 1, v1
	s_add_i32 s0, s3, 6
	v_ashrrev_i32_e32 v33, 31, v32
	s_min_u32 s0, s0, 0x43
	v_lshlrev_b64 v[32:33], 5, v[32:33]
	s_add_i32 s1, s0, -4
	s_sub_i32 s0, 0x43, s0
	v_lshl_or_b32 v30, v2, 4, v55
	s_waitcnt vmcnt(7)
	v_lshl_add_u64 v[42:43], v[6:7], 0, v[32:33]
	v_mov_b32_e32 v2, s0
	v_mov_b32_e32 v32, s1
	v_cndmask_b32_e64 v2, v2, v32, s[4:5]
	v_add_u32_e32 v36, v2, v13
	v_lshl_or_b32 v2, v36, 4, v55
	s_add_i32 s0, s3, 7
	v_lshlrev_b64 v[32:33], 13, v[2:3]
	v_lshl_or_b32 v2, v36, 1, v1
	s_min_u32 s0, s0, 0x43
	v_lshl_add_u64 v[34:35], v[4:5], 0, v[32:33]
	v_lshlrev_b64 v[32:33], 5, v[2:3]
	s_add_i32 s1, s0, -4
	s_sub_i32 s0, 0x43, s0
	v_lshl_add_u64 v[58:59], v[6:7], 0, v[32:33]
	v_mov_b32_e32 v2, s0
	v_mov_b32_e32 v32, s1
	v_cndmask_b32_e64 v2, v2, v32, s[4:5]
	v_add_u32_e32 v2, v2, v13
	v_lshl_or_b32 v32, v2, 4, v55
	v_ashrrev_i32_e32 v33, 31, v32
	v_lshlrev_b64 v[32:33], 13, v[32:33]
	v_lshl_add_u64 v[36:37], v[4:5], 0, v[32:33]
	v_lshl_or_b32 v32, v2, 1, v1
	s_add_i32 s0, s3, 8
	v_ashrrev_i32_e32 v33, 31, v32
	s_min_u32 s1, s0, 0x43
	v_lshlrev_b64 v[32:33], 5, v[32:33]
	s_add_i32 s12, s1, -4
	s_sub_i32 s1, 0x43, s1
	v_lshl_add_u64 v[60:61], v[6:7], 0, v[32:33]
	v_mov_b32_e32 v2, s1
	v_mov_b32_e32 v32, s12
	v_cndmask_b32_e64 v2, v2, v32, s[4:5]
	v_add_u32_e32 v2, v2, v13
	v_lshl_or_b32 v40, v2, 1, v1
	s_add_i32 s1, s3, 9
	v_ashrrev_i32_e32 v41, 31, v40
	s_min_u32 s1, s1, 0x43
	v_lshlrev_b64 v[40:41], 5, v[40:41]
	s_add_i32 s3, s1, -4
	s_sub_i32 s1, 0x43, s1
	v_lshl_or_b32 v32, v2, 4, v55
	v_lshl_add_u64 v[62:63], v[6:7], 0, v[40:41]
	v_mov_b32_e32 v2, s1
	v_mov_b32_e32 v40, s3
	v_cndmask_b32_e64 v2, v2, v40, s[4:5]
	v_add_u32_e32 v2, v2, v13
	v_ashrrev_i32_e32 v31, 31, v30
	v_lshl_or_b32 v40, v2, 4, v55
	v_lshl_or_b32 v56, v2, 1, v1
	v_lshlrev_b64 v[30:31], 13, v[30:31]
	v_ashrrev_i32_e32 v33, 31, v32
	v_ashrrev_i32_e32 v41, 31, v40
	v_ashrrev_i32_e32 v57, 31, v56
	v_lshl_add_u64 v[30:31], v[4:5], 0, v[30:31]
	v_lshlrev_b64 v[32:33], 13, v[32:33]
	v_lshlrev_b64 v[40:41], 13, v[40:41]
	v_lshlrev_b64 v[56:57], 5, v[56:57]
	v_lshl_add_u64 v[38:39], v[4:5], 0, v[32:33]
	global_load_dwordx2 v[52:53], v[30:31], off nt
	global_load_dwordx2 v[48:49], v[34:35], off nt
	global_load_dwordx2 v[44:45], v[36:37], off nt
	global_load_dwordx2 v[32:33], v[38:39], off nt
	v_lshl_add_u64 v[40:41], v[4:5], 0, v[40:41]
	v_lshl_add_u64 v[64:65], v[6:7], 0, v[56:57]
	global_load_dword v56, v[42:43], off
	global_load_dword v54, v[58:59], off
	global_load_dword v50, v[60:61], off
	global_load_dword v46, v[62:63], off
	global_load_dword v2, v[64:65], off
	s_nop 0
	global_load_dwordx2 v[42:43], v[40:41], off nt
	v_cvt_pk_bf16_f32 v58, v8, v9
	v_cvt_pk_bf16_f32 v59, v10, v11
	global_store_dwordx2 v[16:17], v[58:59], off
	s_waitcnt vmcnt(16)
	v_lshlrev_b32_e32 v16, 16, v28
	v_and_b32_e32 v17, 0xffff0000, v28
	s_waitcnt vmcnt(15)
	v_pk_fma_f32 v[8:9], v[8:9], v[26:27], v[16:17] op_sel_hi:[1,0,1]
	v_lshlrev_b32_e32 v16, 16, v29
	v_and_b32_e32 v17, 0xffff0000, v29
	s_cmp_eq_u32 s9, 0
	v_pk_fma_f32 v[10:11], v[10:11], v[26:27], v[16:17] op_sel_hi:[1,0,1]
	s_cbranch_scc1 .LBB0_677
	v_cvt_pk_bf16_f32 v16, v8, v9
	v_cvt_pk_bf16_f32 v17, v10, v11
	s_min_u32 s1, s9, 7
	global_store_dwordx2 v[14:15], v[16:17], off
	s_waitcnt vmcnt(14)
	v_lshlrev_b32_e32 v14, 16, v18
	v_and_b32_e32 v15, 0xffff0000, v18
	s_add_i32 s1, s1, 1
	v_pk_fma_f32 v[8:9], v[8:9], v[12:13], v[14:15] op_sel_hi:[1,0,1]
	v_lshlrev_b32_e32 v14, 16, v19
	v_and_b32_e32 v15, 0xffff0000, v19
	s_cmp_eq_u32 s1, 2
	v_pk_fma_f32 v[10:11], v[10:11], v[12:13], v[14:15] op_sel_hi:[1,0,1]
	s_cbranch_scc1 .LBB0_677
	v_cvt_pk_bf16_f32 v14, v8, v9
	v_cvt_pk_bf16_f32 v15, v10, v11
	global_store_dwordx2 v[22:23], v[14:15], off
	s_waitcnt vmcnt(14)
	v_lshlrev_b32_e32 v14, 16, v24
	v_and_b32_e32 v15, 0xffff0000, v24
	s_waitcnt vmcnt(13)
	v_pk_fma_f32 v[8:9], v[8:9], v[20:21], v[14:15] op_sel_hi:[1,0,1]
	v_lshlrev_b32_e32 v14, 16, v25
	v_and_b32_e32 v15, 0xffff0000, v25
	s_cmp_eq_u32 s1, 3
	v_pk_fma_f32 v[10:11], v[10:11], v[20:21], v[14:15] op_sel_hi:[1,0,1]
	s_cbranch_scc1 .LBB0_677
	v_cvt_pk_bf16_f32 v14, v8, v9
	v_cvt_pk_bf16_f32 v15, v10, v11
	global_store_dwordx2 v[30:31], v[14:15], off
	s_waitcnt vmcnt(13)
	v_lshlrev_b32_e32 v14, 16, v52
	v_and_b32_e32 v15, 0xffff0000, v52
	s_waitcnt vmcnt(9)
	v_pk_fma_f32 v[8:9], v[8:9], v[56:57], v[14:15] op_sel_hi:[1,0,1]
	v_lshlrev_b32_e32 v14, 16, v53
	v_and_b32_e32 v15, 0xffff0000, v53
	s_cmp_eq_u32 s1, 4
	v_pk_fma_f32 v[10:11], v[10:11], v[56:57], v[14:15] op_sel_hi:[1,0,1]
	s_cbranch_scc1 .LBB0_677
	v_cvt_pk_bf16_f32 v14, v8, v9
	v_cvt_pk_bf16_f32 v15, v10, v11
	global_store_dwordx2 v[34:35], v[14:15], off
	v_lshlrev_b32_e32 v14, 16, v48
	v_and_b32_e32 v15, 0xffff0000, v48
	s_waitcnt vmcnt(9)
	v_pk_fma_f32 v[8:9], v[8:9], v[54:55], v[14:15] op_sel_hi:[1,0,1]
	v_lshlrev_b32_e32 v14, 16, v49
	v_and_b32_e32 v15, 0xffff0000, v49
	s_cmp_eq_u32 s1, 5
	v_pk_fma_f32 v[10:11], v[10:11], v[54:55], v[14:15] op_sel_hi:[1,0,1]
	s_cbranch_scc1 .LBB0_677
	v_cvt_pk_bf16_f32 v14, v8, v9
	v_cvt_pk_bf16_f32 v15, v10, v11
	global_store_dwordx2 v[36:37], v[14:15], off
	v_lshlrev_b32_e32 v14, 16, v44
	v_and_b32_e32 v15, 0xffff0000, v44
	s_waitcnt vmcnt(9)
	v_pk_fma_f32 v[8:9], v[8:9], v[50:51], v[14:15] op_sel_hi:[1,0,1]
	v_lshlrev_b32_e32 v14, 16, v45
	v_and_b32_e32 v15, 0xffff0000, v45
	s_cmp_eq_u32 s1, 6
	v_pk_fma_f32 v[10:11], v[10:11], v[50:51], v[14:15] op_sel_hi:[1,0,1]
	s_cbranch_scc1 .LBB0_677
	v_cvt_pk_bf16_f32 v14, v8, v9
	v_cvt_pk_bf16_f32 v15, v10, v11
	global_store_dwordx2 v[38:39], v[14:15], off
	v_lshlrev_b32_e32 v14, 16, v32
	v_and_b32_e32 v15, 0xffff0000, v32
	s_waitcnt vmcnt(9)
	v_pk_fma_f32 v[8:9], v[8:9], v[46:47], v[14:15] op_sel_hi:[1,0,1]
	v_lshlrev_b32_e32 v14, 16, v33
	v_and_b32_e32 v15, 0xffff0000, v33
	s_cmp_eq_u32 s1, 7
	v_pk_fma_f32 v[10:11], v[10:11], v[46:47], v[14:15] op_sel_hi:[1,0,1]
	s_cbranch_scc1 .LBB0_677
	v_cvt_pk_bf16_f32 v14, v8, v9
	v_cvt_pk_bf16_f32 v15, v10, v11
	global_store_dwordx2 v[40:41], v[14:15], off
	s_waitcnt vmcnt(8)
	v_lshlrev_b32_e32 v14, 16, v42
	v_and_b32_e32 v15, 0xffff0000, v42
	v_pk_fma_f32 v[8:9], v[8:9], v[2:3], v[14:15] op_sel_hi:[1,0,1]
	v_lshlrev_b32_e32 v14, 16, v43
	v_and_b32_e32 v15, 0xffff0000, v43
	v_pk_fma_f32 v[10:11], v[10:11], v[2:3], v[14:15] op_sel_hi:[1,0,1]
	s_branch .LBB0_677

; __global__ void __launch_bounds__(NT, 2) fwd_kernel(Args args) {
;     ...
;             const int chain = gt >> 11, b = chain >> 3, h = (chain >> 1) & 3, d = chain & 1, e = 4 * (gt & 2047);
;             float s0 = 0.f, s1 = 0.f, s2 = 0.f, s3 = 0.f;
;             _Pragma("unroll 1") for (int st = 0; st < 72; st += 8) {
;                 v2u loc[8]; f32x4 dec[8]; bf16* ad[8];
; #pragma unroll
;                 for (int u = 0; u < 8; ++u) { const int ch = chain_chunk(b, d, (st + u < 68) ? st + u : 67); ad[u] = STG + (size_t)((ch * 4 + h) * 2 + d) * 8192 + e; loc[u] = *(const v2u*)ad[u];
;                     dec[u] = *(const f32x4*)(DECG + (size_t)(ch * 2 + d) * 256 + h * 64 + (e & 63)); }
.LBB0_693:
	s_cmp_lg_u32 s3, -2
	s_cselect_b64 s[0:1], -1, 0
	s_cmp_eq_u32 s3, -2
	s_cselect_b64 vcc, -1, 0
	s_add_i32 s12, s8, -4
	s_waitcnt vmcnt(13)
	v_mov_b32_e32 v2, s9
	v_mov_b32_e32 v3, s12
	v_cndmask_b32_e64 v2, v2, v3, s[4:5]
	v_add_u32_e32 v2, v2, v74
	v_cndmask_b32_e32 v4, v2, v75, vcc
	v_lshl_or_b32 v2, v4, 3, v79
	v_ashrrev_i32_e32 v3, 31, v2
	v_lshlrev_b64 v[2:3], 14, v[2:3]
	s_add_i32 s12, s8, -3
	s_add_i32 s13, s9, -1
	v_lshl_add_u64 v[46:47], v[36:37], 0, v[2:3]
	v_lshl_or_b32 v2, v4, 1, v1
	v_mov_b32_e32 v4, s13
	v_mov_b32_e32 v5, s12
	v_cndmask_b32_e64 v4, v4, v5, s[4:5]
	v_add_u32_e32 v4, v4, v74
	s_waitcnt vmcnt(11)
	v_cndmask_b32_e32 v6, v4, v76, vcc
	v_lshl_or_b32 v4, v6, 3, v79
	v_ashrrev_i32_e32 v5, 31, v4
	v_lshlrev_b64 v[4:5], 14, v[4:5]
	v_lshl_add_u64 v[44:45], v[36:37], 0, v[4:5]
	v_lshl_or_b32 v4, v6, 1, v1
	v_ashrrev_i32_e32 v3, 31, v2
	v_ashrrev_i32_e32 v5, 31, v4
	v_lshlrev_b64 v[2:3], 10, v[2:3]
	v_lshlrev_b64 v[4:5], 10, v[4:5]
	v_lshl_add_u64 v[2:3], v[38:39], 0, v[2:3]
	v_lshl_add_u64 v[4:5], v[38:39], 0, v[4:5]
	global_load_dwordx2 v[52:53], v[46:47], off nt
	global_load_dwordx2 v[42:43], v[44:45], off nt
	global_load_dwordx4 v[14:17], v[2:3], off
	s_nop 0
	global_load_dwordx4 v[2:5], v[4:5], off
	s_and_b64 vcc, exec, vcc
	v_mov_b32_e32 v6, v77
	s_cbranch_vccnz .LBB0_695
	s_add_i32 s12, s9, -2
	v_mov_b32_e32 v6, s12
	v_mov_b32_e32 v7, s3
	v_cndmask_b32_e64 v6, v6, v7, s[4:5]
	v_add_u32_e32 v6, v6, v74
.LBB0_695:
	v_lshl_or_b32 v8, v6, 3, v79
	v_lshl_or_b32 v6, v6, 1, v1
	v_ashrrev_i32_e32 v9, 31, v8
	v_ashrrev_i32_e32 v7, 31, v6
	v_lshlrev_b64 v[8:9], 14, v[8:9]
	v_lshlrev_b64 v[6:7], 10, v[6:7]
	v_lshl_add_u64 v[50:51], v[36:37], 0, v[8:9]
	v_lshl_add_u64 v[6:7], v[38:39], 0, v[6:7]
	global_load_dwordx2 v[48:49], v[50:51], off nt
	s_nop 0
	global_load_dwordx4 v[6:9], v[6:7], off
	s_andn2_b64 vcc, exec, s[0:1]
	s_waitcnt vmcnt(15)
	v_mov_b32_e32 v10, v78
	s_cbranch_vccnz .LBB0_697
	s_add_i32 s0, s3, 1
	s_add_i32 s1, s9, -3
	v_mov_b32_e32 v10, s1
	v_mov_b32_e32 v11, s0
	v_cndmask_b32_e64 v10, v10, v11, s[4:5]
	v_add_u32_e32 v10, v10, v74
; __device__ __forceinline__ unsigned pk2(float lo, float hi) { const f32x2cv v = {lo, hi}; const bf16x2cv b = __builtin_convertvector(v, bf16x2cv); return __builtin_bit_cast(unsigned, b); }
; __global__ void __launch_bounds__(NT, 2) fwd_kernel(Args args) {
;     ...
;             _Pragma("unroll 1") for (int st = 0; st < 72; st += 8) {
;                 v2u loc[8]; f32x4 dec[8]; bf16* ad[8];
; #pragma unroll
;                 for (int u = 0; u < 8; ++u) { const int ch = chain_chunk(b, d, (st + u < 68) ? st + u : 67); ad[u] = STG + (size_t)((ch * 4 + h) * 2 + d) * 8192 + e; loc[u] = *(const v2u*)ad[u];
;                     dec[u] = *(const f32x4*)(DECG + (size_t)(ch * 2 + d) * 256 + h * 64 + (e & 63)); }
; #pragma unroll
;                 for (int u = 0; u < 8; ++u) { if (st + u >= 68) break; v2u o; o.x = pk2(s0, s1); o.y = pk2(s2, s3); *(v2u*)ad[u] = o;
;                     s0 = s0 * dec[u].x + bflo(loc[u].x); s1 = s1 * dec[u].y + bfhi(loc[u].x); s2 = s2 * dec[u].z + bflo(loc[u].y); s3 = s3 * dec[u].w + bfhi(loc[u].y); }
;             }
.LBB0_697:
	v_lshl_or_b32 v12, v10, 3, v79
	v_lshl_or_b32 v10, v10, 1, v1
	s_add_i32 s0, s3, 6
	v_ashrrev_i32_e32 v11, 31, v10
	s_min_u32 s0, s0, 0x43
	v_lshlrev_b64 v[10:11], 10, v[10:11]
	s_add_i32 s1, s0, -4
	s_sub_i32 s0, 0x43, s0
	v_ashrrev_i32_e32 v13, 31, v12
	s_waitcnt vmcnt(7)
	v_lshl_add_u64 v[18:19], v[38:39], 0, v[10:11]
	v_mov_b32_e32 v10, s0
	v_mov_b32_e32 v11, s1
	v_lshlrev_b64 v[12:13], 14, v[12:13]
	v_cndmask_b32_e64 v10, v10, v11, s[4:5]
	v_lshl_add_u64 v[56:57], v[36:37], 0, v[12:13]
	v_add_u32_e32 v12, v10, v74
	v_lshl_or_b32 v10, v12, 3, v79
	s_add_i32 s0, s3, 7
	v_ashrrev_i32_e32 v11, 31, v10
	s_min_u32 s0, s0, 0x43
	v_lshlrev_b64 v[10:11], 14, v[10:11]
	s_add_i32 s1, s0, -4
	s_sub_i32 s0, 0x43, s0
	v_lshl_add_u64 v[58:59], v[36:37], 0, v[10:11]
	v_lshl_or_b32 v10, v12, 1, v1
	v_mov_b32_e32 v12, s0
	v_mov_b32_e32 v13, s1
	v_cndmask_b32_e64 v12, v12, v13, s[4:5]
	v_add_u32_e32 v20, v12, v74
	v_lshl_or_b32 v12, v20, 3, v79
	s_add_i32 s0, s3, 8
	v_ashrrev_i32_e32 v13, 31, v12
	s_min_u32 s1, s0, 0x43
	v_lshlrev_b64 v[12:13], 14, v[12:13]
	s_add_i32 s12, s1, -4
	s_sub_i32 s1, 0x43, s1
	v_lshl_add_u64 v[62:63], v[36:37], 0, v[12:13]
	v_lshl_or_b32 v12, v20, 1, v1
	v_mov_b32_e32 v20, s1
	v_mov_b32_e32 v21, s12
	v_cndmask_b32_e64 v20, v20, v21, s[4:5]
	v_add_u32_e32 v26, v20, v74
	v_lshl_or_b32 v20, v26, 3, v79
	s_add_i32 s1, s3, 9
	v_ashrrev_i32_e32 v21, 31, v20
	s_min_u32 s1, s1, 0x43
	v_lshlrev_b64 v[20:21], 14, v[20:21]
	s_add_i32 s3, s1, -4
	s_sub_i32 s1, 0x43, s1
	v_lshl_add_u64 v[64:65], v[36:37], 0, v[20:21]
	v_lshl_or_b32 v20, v26, 1, v1
	v_mov_b32_e32 v26, s1
	v_mov_b32_e32 v27, s3
	v_cndmask_b32_e64 v26, v26, v27, s[4:5]
	v_add_u32_e32 v28, v26, v74
	v_ashrrev_i32_e32 v11, 31, v10
	v_ashrrev_i32_e32 v13, 31, v12
	v_lshl_or_b32 v26, v28, 3, v79
	v_lshlrev_b64 v[10:11], 10, v[10:11]
	v_lshlrev_b64 v[12:13], 10, v[12:13]
	v_ashrrev_i32_e32 v27, 31, v26
	v_lshl_add_u64 v[10:11], v[38:39], 0, v[10:11]
	v_lshl_add_u64 v[12:13], v[38:39], 0, v[12:13]
	v_lshlrev_b64 v[26:27], 14, v[26:27]
	global_load_dwordx4 v[22:25], v[10:11], off
	s_nop 0
	global_load_dwordx4 v[10:13], v[12:13], off
	s_nop 0
	global_load_dwordx2 v[72:73], v[56:57], off nt
	global_load_dwordx2 v[70:71], v[58:59], off nt
	global_load_dwordx2 v[68:69], v[62:63], off nt
	global_load_dwordx2 v[54:55], v[64:65], off nt
	v_lshl_add_u64 v[66:67], v[36:37], 0, v[26:27]
	global_load_dwordx4 v[30:33], v[18:19], off
	global_load_dwordx2 v[60:61], v[66:67], off nt
	v_lshl_or_b32 v18, v28, 1, v1
	v_ashrrev_i32_e32 v21, 31, v20
	v_ashrrev_i32_e32 v19, 31, v18
	v_lshlrev_b64 v[20:21], 10, v[20:21]
	v_lshlrev_b64 v[18:19], 10, v[18:19]
	v_lshl_add_u64 v[20:21], v[38:39], 0, v[20:21]
	v_lshl_add_u64 v[18:19], v[38:39], 0, v[18:19]
	global_load_dwordx4 v[26:29], v[20:21], off
	s_nop 0
	global_load_dwordx4 v[18:21], v[18:19], off
	v_cvt_pk_bf16_f32 v80, v34, v35
	v_cvt_pk_bf16_f32 v81, v40, v41
	global_store_dwordx2 v[46:47], v[80:81], off
	s_waitcnt vmcnt(16)
	v_lshlrev_b32_e32 v46, 16, v52
	v_and_b32_e32 v47, 0xffff0000, v52
	s_waitcnt vmcnt(14)
	v_pk_fma_f32 v[34:35], v[34:35], v[14:15], v[46:47]
	v_lshlrev_b32_e32 v14, 16, v53
	v_and_b32_e32 v15, 0xffff0000, v53
	s_cmp_eq_u32 s9, 0
	v_pk_fma_f32 v[40:41], v[40:41], v[16:17], v[14:15]
	s_cbranch_scc1 .LBB0_692
	v_cvt_pk_bf16_f32 v14, v34, v35
	v_cvt_pk_bf16_f32 v15, v40, v41
	s_min_u32 s1, s9, 7
	global_store_dwordx2 v[44:45], v[14:15], off
	v_lshlrev_b32_e32 v14, 16, v42
	v_and_b32_e32 v15, 0xffff0000, v42
	s_add_i32 s1, s1, 1
	s_waitcnt vmcnt(14)
	v_pk_fma_f32 v[34:35], v[34:35], v[2:3], v[14:15]
	v_lshlrev_b32_e32 v2, 16, v43
	v_and_b32_e32 v3, 0xffff0000, v43
	s_cmp_eq_u32 s1, 2
	v_pk_fma_f32 v[40:41], v[40:41], v[4:5], v[2:3]
	s_cbranch_scc1 .LBB0_692
	v_cvt_pk_bf16_f32 v2, v34, v35
	v_cvt_pk_bf16_f32 v3, v40, v41
	global_store_dwordx2 v[50:51], v[2:3], off
	s_waitcnt vmcnt(14)
	v_lshlrev_b32_e32 v2, 16, v48
	v_and_b32_e32 v3, 0xffff0000, v48
	s_waitcnt vmcnt(13)
	v_pk_fma_f32 v[34:35], v[34:35], v[6:7], v[2:3]
	v_lshlrev_b32_e32 v2, 16, v49
	v_and_b32_e32 v3, 0xffff0000, v49
	s_cmp_eq_u32 s1, 3
	v_pk_fma_f32 v[40:41], v[40:41], v[8:9], v[2:3]
	s_cbranch_scc1 .LBB0_692
	v_cvt_pk_bf16_f32 v2, v34, v35
	v_cvt_pk_bf16_f32 v3, v40, v41
	global_store_dwordx2 v[56:57], v[2:3], off
	s_waitcnt vmcnt(11)
	v_lshlrev_b32_e32 v2, 16, v72
	v_and_b32_e32 v3, 0xffff0000, v72
	s_waitcnt vmcnt(7)
	v_pk_fma_f32 v[34:35], v[34:35], v[30:31], v[2:3]
	v_lshlrev_b32_e32 v2, 16, v73
	v_and_b32_e32 v3, 0xffff0000, v73
	s_cmp_eq_u32 s1, 4
	v_pk_fma_f32 v[40:41], v[40:41], v[32:33], v[2:3]
	s_cbranch_scc1 .LBB0_692
	v_cvt_pk_bf16_f32 v2, v34, v35
	v_cvt_pk_bf16_f32 v3, v40, v41
	global_store_dwordx2 v[58:59], v[2:3], off
	v_lshlrev_b32_e32 v2, 16, v70
	v_and_b32_e32 v3, 0xffff0000, v70
	v_pk_fma_f32 v[34:35], v[34:35], v[22:23], v[2:3]
	v_lshlrev_b32_e32 v2, 16, v71
	v_and_b32_e32 v3, 0xffff0000, v71
	s_cmp_eq_u32 s1, 5
	v_pk_fma_f32 v[40:41], v[40:41], v[24:25], v[2:3]
	s_cbranch_scc1 .LBB0_692
	v_cvt_pk_bf16_f32 v2, v34, v35
	v_cvt_pk_bf16_f32 v3, v40, v41
	global_store_dwordx2 v[62:63], v[2:3], off
	v_lshlrev_b32_e32 v2, 16, v68
	v_and_b32_e32 v3, 0xffff0000, v68
	v_pk_fma_f32 v[34:35], v[34:35], v[10:11], v[2:3]
	v_lshlrev_b32_e32 v2, 16, v69
	v_and_b32_e32 v3, 0xffff0000, v69
	s_cmp_eq_u32 s1, 6
	v_pk_fma_f32 v[40:41], v[40:41], v[12:13], v[2:3]
	s_cbranch_scc1 .LBB0_692
	v_cvt_pk_bf16_f32 v2, v34, v35
	v_cvt_pk_bf16_f32 v3, v40, v41
	global_store_dwordx2 v[64:65], v[2:3], off
	v_lshlrev_b32_e32 v2, 16, v54
	v_and_b32_e32 v3, 0xffff0000, v54
	s_waitcnt vmcnt(8)
	v_pk_fma_f32 v[34:35], v[34:35], v[26:27], v[2:3]
	v_lshlrev_b32_e32 v2, 16, v55
	v_and_b32_e32 v3, 0xffff0000, v55
	s_cmp_eq_u32 s1, 7
	v_pk_fma_f32 v[40:41], v[40:41], v[28:29], v[2:3]
	s_cbranch_scc1 .LBB0_692
	v_cvt_pk_bf16_f32 v2, v34, v35
	v_cvt_pk_bf16_f32 v3, v40, v41
	global_store_dwordx2 v[66:67], v[2:3], off
	v_lshlrev_b32_e32 v2, 16, v60
	v_and_b32_e32 v3, 0xffff0000, v60
	s_waitcnt vmcnt(8)
	v_pk_fma_f32 v[34:35], v[34:35], v[18:19], v[2:3]
	v_lshlrev_b32_e32 v2, 16, v61
	v_and_b32_e32 v3, 0xffff0000, v61
	v_pk_fma_f32 v[40:41], v[40:41], v[20:21], v[2:3]
	s_branch .LBB0_692

;     __device__ __forceinline__ void fused(f32x4 (&acc)[2][2][4][2], const Unit& u, int wr, int wc, int fr, int fq, PG8_LAS unsigned char* lds, int wid, int lane) const {
;     ...
;         for (int ai = 0; ai < 2; ++ai)
; #pragma unroll
;             for (int m = 0; m < 4; ++m) { const int r = ai * HALF + wr * 64 + m * 16 + fr; const f32x2v sr = S[r]; const size_t off = (size_t)(u.pm * BM + r) * ldc + col0;
; #pragma unroll
;                 for (int bj = 0; bj < 2; ++bj)
; #pragma unroll
;                     for (int n = 0; n < 2; ++n) { const f32x4 bs = *(const f32x4*)(base + off + bj * HALF + n * 16); acc[ai][bj][m][n] = bs + cvv[bj][n] * (acc[ai][bj][m][n] * sr.y); }
;                 asm volatile("" : "+v"(acc[ai][0][m][0]), "+v"(acc[ai][0][m][1]), "+v"(acc[ai][1][m][0]), "+v"(acc[ai][1][m][1]));
;                 if (m & 1) asm volatile("" ::: "memory"); }
.LBB0_1073:
	s_or_b64 exec, exec, s[0:1]
	v_add_u32_e32 v150, s3, v152
	v_readlane_b32 s36, v240, 11
	v_ashrrev_i32_e32 v151, 31, v150
	v_readlane_b32 s37, v240, 12
	v_lshlrev_b64 v[154:155], 12, v[150:151]
	s_mov_b64 s[0:1], s[36:37]
	v_lshl_add_u64 v[154:155], s[0:1], 0, v[154:155]
	v_lshlrev_b64 v[168:169], 2, v[162:163]
	s_waitcnt lgkmcnt(0)
	s_barrier
	v_lshl_add_u64 v[174:175], v[154:155], 0, v[168:169]
	global_load_dwordx4 v[154:157], v[174:175], off nt
	global_load_dwordx4 v[158:161], v[174:175], off offset:64 nt
	global_load_dwordx4 v[164:167], v[174:175], off offset:512 nt
	s_nop 0
	global_load_dwordx4 v[174:177], v[174:175], off offset:576 nt
	v_lshl_add_u32 v182, v152, 3, 0
	ds_read_b64 v[178:179], v182 offset:8192
	v_add_u32_e32 v152, 16, v150
	s_waitcnt lgkmcnt(0)
	v_ashrrev_i32_e32 v153, 31, v152
	v_lshlrev_b64 v[180:181], 12, v[152:153]
	v_lshl_add_u64 v[180:181], s[0:1], 0, v[180:181]
	v_pk_mul_f32 v[128:129], v[128:129], v[178:179] op_sel:[0,1]
	v_pk_mul_f32 v[126:127], v[126:127], v[178:179] op_sel:[0,1]
	v_pk_mul_f32 v[124:125], v[124:125], v[178:179] op_sel:[0,1]
	v_pk_mul_f32 v[122:123], v[122:123], v[178:179] op_sel:[0,1]
	v_pk_mul_f32 v[186:187], v[120:121], v[178:179] op_sel:[0,1]
	v_pk_mul_f32 v[188:189], v[118:119], v[178:179] op_sel:[0,1]
	v_pk_mul_f32 v[190:191], v[116:117], v[178:179] op_sel:[0,1]
	v_pk_mul_f32 v[178:179], v[114:115], v[178:179] op_sel:[0,1]
	v_lshl_add_u64 v[180:181], v[180:181], 0, v[168:169]
	v_readlane_b32 s38, v240, 13
	v_readlane_b32 s39, v240, 14
	v_readlane_b32 s40, v240, 15
	v_readlane_b32 s41, v240, 16
	v_readlane_b32 s42, v240, 17
	v_readlane_b32 s43, v240, 18
	v_readlane_b32 s44, v240, 19
	v_readlane_b32 s45, v240, 20
	v_readlane_b32 s46, v240, 21
	v_readlane_b32 s47, v240, 22
	v_readlane_b32 s48, v240, 23
	v_readlane_b32 s49, v240, 24
	v_readlane_b32 s50, v240, 25
	v_readlane_b32 s51, v240, 26
	s_waitcnt vmcnt(0)
	v_pk_fma_f32 v[114:115], v[142:143], v[126:127], v[154:155]
	v_pk_fma_f32 v[116:117], v[144:145], v[128:129], v[156:157]
	v_pk_fma_f32 v[118:119], v[138:139], v[122:123], v[158:159]
	v_pk_fma_f32 v[120:121], v[140:141], v[124:125], v[160:161]
	v_pk_fma_f32 v[122:123], v[134:135], v[188:189], v[164:165]
	v_pk_fma_f32 v[124:125], v[136:137], v[186:187], v[166:167]
	v_pk_fma_f32 v[126:127], v[130:131], v[178:179], v[174:175]
	v_pk_fma_f32 v[128:129], v[132:133], v[190:191], v[176:177]
	v_add_u32_e32 v154, 32, v150
	global_load_dwordx4 v[156:159], v[180:181], off nt
	global_load_dwordx4 v[164:167], v[180:181], off offset:64 nt
	global_load_dwordx4 v[174:177], v[180:181], off offset:512 nt
	s_nop 0
	global_load_dwordx4 v[178:181], v[180:181], off offset:576 nt
	ds_read_b64 v[160:161], v182 offset:8320
	v_ashrrev_i32_e32 v155, 31, v154
	v_lshlrev_b64 v[186:187], 12, v[154:155]
	v_lshl_add_u64 v[186:187], s[0:1], 0, v[186:187]
	v_lshl_add_u64 v[186:187], v[186:187], 0, v[168:169]
	s_waitcnt lgkmcnt(0)
	v_pk_mul_f32 v[112:113], v[112:113], v[160:161] op_sel:[0,1]
	v_pk_mul_f32 v[110:111], v[110:111], v[160:161] op_sel:[0,1]
	v_pk_mul_f32 v[108:109], v[108:109], v[160:161] op_sel:[0,1]
	v_pk_mul_f32 v[106:107], v[106:107], v[160:161] op_sel:[0,1]
	v_pk_mul_f32 v[104:105], v[104:105], v[160:161] op_sel:[0,1]
	v_pk_mul_f32 v[102:103], v[102:103], v[160:161] op_sel:[0,1]
	v_pk_mul_f32 v[100:101], v[100:101], v[160:161] op_sel:[0,1]
	v_pk_mul_f32 v[98:99], v[98:99], v[160:161] op_sel:[0,1]
	v_mov_b32_e32 v196, v114
	v_mov_b32_e32 v197, v117
	v_mov_b32_e32 v198, v119
	v_mov_b32_e32 v199, v120
	v_mov_b32_e32 v200, v118
	v_mov_b32_e32 v201, v121
	v_add_f32_e32 v203, v122, v123
	v_add_f32_e32 v207, v124, v125
	v_mov_b32_e32 v202, v126
	v_mov_b32_e32 v206, v127
	v_mov_b32_e32 v208, v129
	s_waitcnt vmcnt(3)
	v_pk_fma_f32 v[110:111], v[142:143], v[110:111], v[156:157]
	v_pk_fma_f32 v[112:113], v[144:145], v[112:113], v[158:159]
	s_waitcnt vmcnt(2)
	v_pk_fma_f32 v[106:107], v[138:139], v[106:107], v[164:165]
	v_pk_fma_f32 v[108:109], v[140:141], v[108:109], v[166:167]
	s_waitcnt vmcnt(1)
	v_pk_fma_f32 v[102:103], v[134:135], v[102:103], v[174:175]
	v_pk_fma_f32 v[104:105], v[136:137], v[104:105], v[176:177]
	s_waitcnt vmcnt(0)
	v_pk_fma_f32 v[98:99], v[130:131], v[98:99], v[178:179]
	v_pk_fma_f32 v[100:101], v[132:133], v[100:101], v[180:181]
	v_add_u32_e32 v156, 48, v150
	global_load_dwordx4 v[158:161], v[186:187], off nt
	global_load_dwordx4 v[164:167], v[186:187], off offset:64 nt
	global_load_dwordx4 v[174:177], v[186:187], off offset:512 nt
	global_load_dwordx4 v[178:181], v[186:187], off offset:576 nt
	ds_read_b64 v[186:187], v182 offset:8448
	v_ashrrev_i32_e32 v157, 31, v156
	v_lshlrev_b64 v[188:189], 12, v[156:157]
	v_lshl_add_u64 v[188:189], s[0:1], 0, v[188:189]
	v_lshl_add_u64 v[188:189], v[188:189], 0, v[168:169]
	s_waitcnt lgkmcnt(0)
	v_pk_mul_f32 v[96:97], v[96:97], v[186:187] op_sel:[0,1]
	v_pk_mul_f32 v[94:95], v[94:95], v[186:187] op_sel:[0,1]
	v_pk_mul_f32 v[92:93], v[92:93], v[186:187] op_sel:[0,1]
	v_pk_mul_f32 v[90:91], v[90:91], v[186:187] op_sel:[0,1]
	v_pk_mul_f32 v[88:89], v[88:89], v[186:187] op_sel:[0,1]
	v_pk_mul_f32 v[86:87], v[86:87], v[186:187] op_sel:[0,1]
	v_pk_mul_f32 v[84:85], v[84:85], v[186:187] op_sel:[0,1]
	v_pk_mul_f32 v[82:83], v[82:83], v[186:187] op_sel:[0,1]
	s_waitcnt vmcnt(3)
	v_pk_fma_f32 v[94:95], v[142:143], v[94:95], v[158:159]
	v_pk_fma_f32 v[96:97], v[144:145], v[96:97], v[160:161]
	s_waitcnt vmcnt(2)
	v_pk_fma_f32 v[90:91], v[138:139], v[90:91], v[164:165]
	v_pk_fma_f32 v[92:93], v[140:141], v[92:93], v[166:167]
	s_waitcnt vmcnt(1)
	v_pk_fma_f32 v[86:87], v[134:135], v[86:87], v[174:175]
	v_pk_fma_f32 v[88:89], v[136:137], v[88:89], v[176:177]
	s_waitcnt vmcnt(0)
;     __device__ __forceinline__ void fused(f32x4 (&acc)[2][2][4][2], const Unit& u, int wr, int wc, int fr, int fq, PG8_LAS unsigned char* lds, int wid, int lane) const {
;     ...
;         for (int ai = 0; ai < 2; ++ai)
; #pragma unroll
;             for (int m = 0; m < 4; ++m) { const int r = ai * HALF + wr * 64 + m * 16 + fr; const f32x2v sr = S[r]; const size_t off = (size_t)(u.pm * BM + r) * ldc + col0;
; #pragma unroll
;                 for (int bj = 0; bj < 2; ++bj)
; #pragma unroll
;                     for (int n = 0; n < 2; ++n) { const f32x4 bs = *(const f32x4*)(base + off + bj * HALF + n * 16); acc[ai][bj][m][n] = bs + cvv[bj][n] * (acc[ai][bj][m][n] * sr.y); }
;                 asm volatile("" : "+v"(acc[ai][0][m][0]), "+v"(acc[ai][0][m][1]), "+v"(acc[ai][1][m][0]), "+v"(acc[ai][1][m][1]));
;                 if (m & 1) asm volatile("" ::: "memory"); }
	v_pk_fma_f32 v[82:83], v[130:131], v[82:83], v[178:179]
	v_pk_fma_f32 v[84:85], v[132:133], v[84:85], v[180:181]
	v_add_u32_e32 v158, 0x80, v150
	global_load_dwordx4 v[164:167], v[188:189], off nt
	global_load_dwordx4 v[174:177], v[188:189], off offset:64 nt
	global_load_dwordx4 v[178:181], v[188:189], off offset:512 nt
	s_nop 0
	global_load_dwordx4 v[186:189], v[188:189], off offset:576 nt
	ds_read_b64 v[160:161], v182 offset:8576
	v_ashrrev_i32_e32 v159, 31, v158
	v_lshlrev_b64 v[190:191], 12, v[158:159]
	v_lshl_add_u64 v[190:191], s[0:1], 0, v[190:191]
	v_lshl_add_u64 v[190:191], v[190:191], 0, v[168:169]
	s_waitcnt lgkmcnt(0)
	v_pk_mul_f32 v[80:81], v[80:81], v[160:161] op_sel:[0,1]
	v_pk_mul_f32 v[78:79], v[78:79], v[160:161] op_sel:[0,1]
	v_pk_mul_f32 v[76:77], v[76:77], v[160:161] op_sel:[0,1]
	v_pk_mul_f32 v[74:75], v[74:75], v[160:161] op_sel:[0,1]
	v_pk_mul_f32 v[72:73], v[72:73], v[160:161] op_sel:[0,1]
	v_pk_mul_f32 v[70:71], v[70:71], v[160:161] op_sel:[0,1]
	v_pk_mul_f32 v[68:69], v[68:69], v[160:161] op_sel:[0,1]
	v_pk_mul_f32 v[66:67], v[66:67], v[160:161] op_sel:[0,1]
	v_add_u32_e32 v160, 0x90, v150
	v_ashrrev_i32_e32 v161, 31, v160
	v_lshlrev_b64 v[192:193], 12, v[160:161]
	v_lshl_add_u64 v[192:193], s[0:1], 0, v[192:193]
	v_lshl_add_u64 v[192:193], v[192:193], 0, v[168:169]
	s_waitcnt vmcnt(3)
	v_pk_fma_f32 v[78:79], v[142:143], v[78:79], v[164:165]
	v_pk_fma_f32 v[80:81], v[144:145], v[80:81], v[166:167]
	s_waitcnt vmcnt(2)
	v_pk_fma_f32 v[74:75], v[138:139], v[74:75], v[174:175]
	v_pk_fma_f32 v[76:77], v[140:141], v[76:77], v[176:177]
	s_waitcnt vmcnt(1)
	v_pk_fma_f32 v[70:71], v[134:135], v[70:71], v[178:179]
	v_pk_fma_f32 v[72:73], v[136:137], v[72:73], v[180:181]
	s_waitcnt vmcnt(0)
	v_pk_fma_f32 v[66:67], v[130:131], v[66:67], v[186:187]
	v_pk_fma_f32 v[68:69], v[132:133], v[68:69], v[188:189]
	s_nop 0
	global_load_dwordx4 v[164:167], v[190:191], off nt
	global_load_dwordx4 v[174:177], v[190:191], off offset:64 nt
	global_load_dwordx4 v[178:181], v[190:191], off offset:512 nt
	global_load_dwordx4 v[186:189], v[190:191], off offset:576 nt
	ds_read_b64 v[190:191], v182 offset:9216
	s_waitcnt lgkmcnt(0)
	v_pk_mul_f32 v[64:65], v[64:65], v[190:191] op_sel:[0,1]
	v_pk_mul_f32 v[62:63], v[62:63], v[190:191] op_sel:[0,1]
	v_pk_mul_f32 v[60:61], v[60:61], v[190:191] op_sel:[0,1]
	v_pk_mul_f32 v[58:59], v[58:59], v[190:191] op_sel:[0,1]
	v_pk_mul_f32 v[56:57], v[56:57], v[190:191] op_sel:[0,1]
	v_pk_mul_f32 v[54:55], v[54:55], v[190:191] op_sel:[0,1]
	v_pk_mul_f32 v[52:53], v[52:53], v[190:191] op_sel:[0,1]
	v_pk_mul_f32 v[50:51], v[50:51], v[190:191] op_sel:[0,1]
	s_waitcnt vmcnt(3)
	v_pk_fma_f32 v[62:63], v[142:143], v[62:63], v[164:165]
	v_pk_fma_f32 v[64:65], v[144:145], v[64:65], v[166:167]
	s_waitcnt vmcnt(2)
	v_pk_fma_f32 v[58:59], v[138:139], v[58:59], v[174:175]
	v_pk_fma_f32 v[60:61], v[140:141], v[60:61], v[176:177]
	s_waitcnt vmcnt(1)
	v_pk_fma_f32 v[54:55], v[134:135], v[54:55], v[178:179]
	v_pk_fma_f32 v[56:57], v[136:137], v[56:57], v[180:181]
	s_waitcnt vmcnt(0)
	v_pk_fma_f32 v[50:51], v[130:131], v[50:51], v[186:187]
	v_pk_fma_f32 v[52:53], v[132:133], v[52:53], v[188:189]
	v_add_u32_e32 v164, 0xa0, v150
	global_load_dwordx4 v[174:177], v[192:193], off nt
	global_load_dwordx4 v[178:181], v[192:193], off offset:64 nt
	global_load_dwordx4 v[186:189], v[192:193], off offset:512 nt
	s_nop 0
	global_load_dwordx4 v[190:193], v[192:193], off offset:576 nt
	ds_read_b64 v[166:167], v182 offset:9344
	v_ashrrev_i32_e32 v165, 31, v164
	v_lshlrev_b64 v[194:195], 12, v[164:165]
	v_lshl_add_u64 v[194:195], s[0:1], 0, v[194:195]
	v_lshl_add_u64 v[194:195], v[194:195], 0, v[168:169]
	s_waitcnt lgkmcnt(0)
	v_pk_mul_f32 v[48:49], v[48:49], v[166:167] op_sel:[0,1]
	v_pk_mul_f32 v[46:47], v[46:47], v[166:167] op_sel:[0,1]
	v_pk_mul_f32 v[44:45], v[44:45], v[166:167] op_sel:[0,1]
	v_pk_mul_f32 v[42:43], v[42:43], v[166:167] op_sel:[0,1]
	v_pk_mul_f32 v[40:41], v[40:41], v[166:167] op_sel:[0,1]
	v_pk_mul_f32 v[38:39], v[38:39], v[166:167] op_sel:[0,1]
	v_pk_mul_f32 v[36:37], v[36:37], v[166:167] op_sel:[0,1]
	v_pk_mul_f32 v[34:35], v[34:35], v[166:167] op_sel:[0,1]
	v_add_u32_e32 v166, 0xb0, v150
	v_ashrrev_i32_e32 v167, 31, v166
	s_waitcnt vmcnt(3)
	v_pk_fma_f32 v[46:47], v[142:143], v[46:47], v[174:175]
	v_pk_fma_f32 v[48:49], v[144:145], v[48:49], v[176:177]
	s_waitcnt vmcnt(2)
	v_pk_fma_f32 v[42:43], v[138:139], v[42:43], v[178:179]
	v_pk_fma_f32 v[44:45], v[140:141], v[44:45], v[180:181]
	s_waitcnt vmcnt(1)
	v_pk_fma_f32 v[38:39], v[134:135], v[38:39], v[186:187]
	v_pk_fma_f32 v[40:41], v[136:137], v[40:41], v[188:189]
	s_waitcnt vmcnt(0)
	v_pk_fma_f32 v[34:35], v[130:131], v[34:35], v[190:191]
	v_pk_fma_f32 v[36:37], v[132:133], v[36:37], v[192:193]
	s_nop 0
	global_load_dwordx4 v[174:177], v[194:195], off nt
	global_load_dwordx4 v[178:181], v[194:195], off offset:64 nt
	global_load_dwordx4 v[186:189], v[194:195], off offset:512 nt
	global_load_dwordx4 v[190:193], v[194:195], off offset:576 nt
	ds_read_b64 v[204:205], v182 offset:9472
	v_lshlrev_b64 v[194:195], 12, v[166:167]
	v_lshl_add_u64 v[194:195], s[0:1], 0, v[194:195]
	v_lshl_add_u64 v[168:169], v[194:195], 0, v[168:169]
	v_mov_b32_e32 v194, v115
	s_waitcnt lgkmcnt(0)
;     __device__ __forceinline__ bool run(const f32x4 (&v)[2][2][4][2], const Unit& u, int wr, int wc, int fr, int fq, PG8_LAS unsigned char* lds, int wid, int lane) const {
;     ...
;                 float s = 0.f;
; #pragma unroll
;                 for (int bj = 0; bj < 2; ++bj)
; #pragma unroll
;                     for (int n = 0; n < 2; ++n) { const f32x4 x = v[ai][bj][m][n]; s += (x[0] + x[1]) + (x[2] + x[3]); }
;                 s += __shfl_xor(s, 16); s += __shfl_xor(s, 32);
;                 const float mw = s * (1.0f / 64.0f); float q = 0.f;
; #pragma unroll
;                 for (int bj = 0; bj < 2; ++bj)
; #pragma unroll
;                     for (int n = 0; n < 2; ++n) { const f32x4 d = v[ai][bj][m][n] - mw; q += (d[0] * d[0] + d[1] * d[1]) + (d[2] * d[2] + d[3] * d[3]); }
;                 q += __shfl_xor(q, 16); q += __shfl_xor(q, 32);
;                 if (fq == 0) P[(ai * HALF + wr * 64 + m * 16 + fr) * 4 + wc] = (f32x2v){mw, q};
;     __device__ __forceinline__ void fused(f32x4 (&acc)[2][2][4][2], const Unit& u, int wr, int wc, int fr, int fq, PG8_LAS unsigned char* lds, int wid, int lane) const {
;     ...
;         for (int ai = 0; ai < 2; ++ai)
; #pragma unroll
;             for (int m = 0; m < 4; ++m) { const int r = ai * HALF + wr * 64 + m * 16 + fr; const f32x2v sr = S[r]; const size_t off = (size_t)(u.pm * BM + r) * ldc + col0;
; #pragma unroll
;                 for (int bj = 0; bj < 2; ++bj)
; #pragma unroll
;                     for (int n = 0; n < 2; ++n) { const f32x4 bs = *(const f32x4*)(base + off + bj * HALF + n * 16); acc[ai][bj][m][n] = bs + cvv[bj][n] * (acc[ai][bj][m][n] * sr.y); }
;                 asm volatile("" : "+v"(acc[ai][0][m][0]), "+v"(acc[ai][0][m][1]), "+v"(acc[ai][1][m][0]), "+v"(acc[ai][1][m][1]));
;                 if (m & 1) asm volatile("" ::: "memory"); }
	v_pk_mul_f32 v[32:33], v[32:33], v[204:205] op_sel:[0,1]
	v_pk_mul_f32 v[30:31], v[30:31], v[204:205] op_sel:[0,1]
	v_pk_mul_f32 v[28:29], v[28:29], v[204:205] op_sel:[0,1]
	v_pk_mul_f32 v[26:27], v[26:27], v[204:205] op_sel:[0,1]
	v_pk_mul_f32 v[24:25], v[24:25], v[204:205] op_sel:[0,1]
	v_pk_mul_f32 v[22:23], v[22:23], v[204:205] op_sel:[0,1]
	v_pk_mul_f32 v[20:21], v[20:21], v[204:205] op_sel:[0,1]
	v_pk_mul_f32 v[18:19], v[18:19], v[204:205] op_sel:[0,1]
	v_mov_b32_e32 v195, v116
	s_waitcnt vmcnt(3)
	v_pk_fma_f32 v[30:31], v[142:143], v[30:31], v[174:175]
	v_pk_fma_f32 v[32:33], v[144:145], v[32:33], v[176:177]
	s_waitcnt vmcnt(2)
	v_pk_fma_f32 v[26:27], v[138:139], v[26:27], v[178:179]
	v_pk_fma_f32 v[28:29], v[140:141], v[28:29], v[180:181]
	s_waitcnt vmcnt(1)
	v_pk_fma_f32 v[22:23], v[134:135], v[22:23], v[186:187]
	v_pk_fma_f32 v[24:25], v[136:137], v[24:25], v[188:189]
	s_waitcnt vmcnt(0)
	v_pk_fma_f32 v[18:19], v[130:131], v[18:19], v[190:191]
	v_pk_fma_f32 v[20:21], v[132:133], v[20:21], v[192:193]
	v_pk_add_f32 v[174:175], v[194:195], v[196:197]
	global_load_dwordx4 v[176:179], v[168:169], off nt
	global_load_dwordx4 v[186:189], v[168:169], off offset:64 nt
	global_load_dwordx4 v[190:193], v[168:169], off offset:512 nt
	global_load_dwordx4 v[194:197], v[168:169], off offset:576 nt
	v_pk_add_f32 v[180:181], v[198:199], v[200:201]
	v_add_f32_e32 v174, v174, v175
	v_pk_add_f32 v[168:169], v[180:181], v[180:181] op_sel_hi:[0,1]
	v_add_f32_e32 v209, 0, v174
	v_mov_b32_e32 v168, v128
	v_pk_add_f32 v[198:199], v[202:203], v[206:207]
	v_pk_add_f32 v[168:169], v[168:169], v[208:209]
	s_nop 0
	v_pk_add_f32 v[168:169], v[198:199], v[168:169]
	s_nop 0
	v_add_f32_e32 v168, v168, v169
	ds_bpermute_b32 v169, v171, v168
	s_waitcnt lgkmcnt(0)
	v_add_f32_e32 v168, v168, v169
	ds_bpermute_b32 v169, v172, v168
	s_waitcnt lgkmcnt(0)
	v_add_f32_e32 v168, v168, v169
	v_fmamk_f32 v174, v168, 0xbc800000, v117
	v_fmamk_f32 v180, v168, 0xbc800000, v115
	v_fmamk_f32 v185, v168, 0xbc800000, v121
	v_fmamk_f32 v199, v168, 0xbc800000, v119
	v_fmamk_f32 v169, v168, 0xbc800000, v116
	v_fmamk_f32 v175, v168, 0xbc800000, v114
	v_fmamk_f32 v181, v168, 0xbc800000, v120
	v_fmamk_f32 v198, v168, 0xbc800000, v118
	v_fmamk_f32 v201, v168, 0xbc800000, v125
	v_fmamk_f32 v203, v168, 0xbc800000, v123
	v_mul_f32_e32 v180, v180, v180
	v_mul_f32_e32 v174, v174, v174
	v_mul_f32_e32 v199, v199, v199
	v_mul_f32_e32 v185, v185, v185
	v_fmamk_f32 v200, v168, 0xbc800000, v124
	v_fmamk_f32 v202, v168, 0xbc800000, v122
	v_fmamk_f32 v205, v168, 0xbc800000, v129
	v_fmamk_f32 v207, v168, 0xbc800000, v127
	v_mul_f32_e32 v203, v203, v203
	v_mul_f32_e32 v201, v201, v201
	v_fmac_f32_e32 v180, v175, v175
	v_fmac_f32_e32 v174, v169, v169
	v_fmac_f32_e32 v199, v198, v198
	v_fmac_f32_e32 v185, v181, v181
	v_fmamk_f32 v204, v168, 0xbc800000, v128
	v_fmamk_f32 v206, v168, 0xbc800000, v126
	v_mul_f32_e32 v207, v207, v207
	v_mul_f32_e32 v205, v205, v205
	v_fmac_f32_e32 v203, v202, v202
	v_fmac_f32_e32 v201, v200, v200
	v_add_f32_e32 v169, v180, v174
	v_add_f32_e32 v174, v199, v185
	v_fmac_f32_e32 v207, v206, v206
	v_fmac_f32_e32 v205, v204, v204
	v_add_f32_e32 v175, v203, v201
	v_add_f32_e32 v169, v169, v174
	v_add_f32_e32 v180, v207, v205
	v_add_f32_e32 v169, v175, v169
	v_add_f32_e32 v169, v180, v169
	ds_bpermute_b32 v174, v171, v169
	ds_read_b64 v[180:181], v182 offset:9600
	s_waitcnt lgkmcnt(1)
	v_add_f32_e32 v169, v169, v174
	ds_bpermute_b32 v174, v172, v169
	s_waitcnt lgkmcnt(1)
	v_pk_mul_f32 v[16:17], v[16:17], v[180:181] op_sel:[0,1]
	v_pk_mul_f32 v[14:15], v[14:15], v[180:181] op_sel:[0,1]
	v_pk_mul_f32 v[12:13], v[12:13], v[180:181] op_sel:[0,1]
	v_pk_mul_f32 v[10:11], v[10:11], v[180:181] op_sel:[0,1]
	v_pk_mul_f32 v[8:9], v[8:9], v[180:181] op_sel:[0,1]
	v_pk_mul_f32 v[6:7], v[6:7], v[180:181] op_sel:[0,1]
	v_pk_mul_f32 v[4:5], v[4:5], v[180:181] op_sel:[0,1]
	v_pk_mul_f32 v[2:3], v[2:3], v[180:181] op_sel:[0,1]
	s_waitcnt vmcnt(3)
	v_pk_fma_f32 v[14:15], v[142:143], v[14:15], v[176:177]
	v_pk_fma_f32 v[16:17], v[144:145], v[16:17], v[178:179]
	s_waitcnt vmcnt(2)
	v_pk_fma_f32 v[10:11], v[138:139], v[10:11], v[186:187]
	v_pk_fma_f32 v[12:13], v[140:141], v[12:13], v[188:189]
	s_waitcnt vmcnt(1)
	v_pk_fma_f32 v[6:7], v[134:135], v[6:7], v[190:191]
	v_pk_fma_f32 v[8:9], v[136:137], v[8:9], v[192:193]
	s_waitcnt vmcnt(0)
	v_pk_fma_f32 v[2:3], v[130:131], v[2:3], v[194:195]
	v_pk_fma_f32 v[4:5], v[132:133], v[4:5], v[196:197]
	s_nop 0
	s_and_saveexec_b64 s[0:1], s[4:5]
	s_cbranch_execz .LBB0_1075
	s_lshl_b32 s3, s52, 11
	s_add_i32 s3, s29, s3
	v_mul_f32_e32 v130, 0x3c800000, v168
	v_lshl_add_u32 v132, v170, 5, s3
	s_waitcnt lgkmcnt(0)
	v_add_f32_e32 v131, v169, v174
	ds_write_b64 v132, v[130:131]

;     __device__ __forceinline__ bool run(const f32x4 (&v)[2][2][4][2], const Unit& u, int wr, int wc, int fr, int fq, PG8_LAS unsigned char* lds, int wid, int lane) const {
;     ...
;         for (int ai = 0; ai < 2; ++ai)
; #pragma unroll
;             for (int m = 0; m < 4; ++m) {
;                 float s = 0.f;
; #pragma unroll
;                 for (int bj = 0; bj < 2; ++bj)
; #pragma unroll
;                     for (int n = 0; n < 2; ++n) { const f32x4 x = v[ai][bj][m][n]; s += (x[0] + x[1]) + (x[2] + x[3]); }
;                 s += __shfl_xor(s, 16); s += __shfl_xor(s, 32);
;                 const float mw = s * (1.0f / 64.0f); float q = 0.f;
; #pragma unroll
;                 for (int bj = 0; bj < 2; ++bj)
; #pragma unroll
;                     for (int n = 0; n < 2; ++n) { const f32x4 d = v[ai][bj][m][n] - mw; q += (d[0] * d[0] + d[1] * d[1]) + (d[2] * d[2] + d[3] * d[3]); }
;                 q += __shfl_xor(q, 16); q += __shfl_xor(q, 32);
;                 if (fq == 0) P[(ai * HALF + wr * 64 + m * 16 + fr) * 4 + wc] = (f32x2v){mw, q};
;     __device__ __forceinline__ void fused(f32x4 (&acc)[2][2][4][2], const Unit& u, int wr, int wc, int fr, int fq, PG8_LAS unsigned char* lds, int wid, int lane) const {
;     ...
;         const int col0 = u.pn * BM + wc * 32 + 4 * fq;
;         const float* cv = colv + (size_t)(u.pm >> 4) * 4096 + col0;
;         f32x4 cvv[2][2];
; #pragma unroll
;         for (int bj = 0; bj < 2; ++bj)
; #pragma unroll
;             for (int n = 0; n < 2; ++n) cvv[bj][n] = *(const f32x4*)(cv + bj * HALF + n * 16);
;         f32x4 pre[4][2][2];
; #pragma unroll
;         for (int m = 0; m < 4; ++m) { const size_t off = (size_t)(u.pm * BM + wr * 64 + m * 16 + fr) * ldc + col0;
; #pragma unroll
;             for (int bj = 0; bj < 2; ++bj)
; #pragma unroll
;                 for (int n = 0; n < 2; ++n) pre[m][bj][n] = *(const f32x4*)(base + off + bj * HALF + n * 16); }
.LBB0_1264:
	s_lshl_b32 s0, s34, 5
	s_lshl_b32 s1, s12, 8
	s_or_b32 s0, s1, s0
	v_lshrrev_b32_e32 v130, 2, v0
	v_and_or_b32 v210, v130, 12, s0
	s_ashr_i32 s0, s31, 4
	s_ashr_i32 s1, s0, 31
	s_lshl_b64 s[0:1], s[0:1], 14
	s_add_u32 s0, s78, s0
	v_ashrrev_i32_e32 v211, 31, v210
	s_addc_u32 s1, s79, s1
	v_lshlrev_b64 v[214:215], 2, v[210:211]
	v_lshl_add_u64 v[130:131], s[0:1], 0, v[214:215]
	s_mov_b64 s[0:1], 0xe43000
	v_lshl_add_u64 v[132:133], v[130:131], 0, s[0:1]
	s_mov_b32 s0, 0xe43000
	s_lshl_b32 s16, s31, 8
	v_add_co_u32_e32 v130, vcc, s0, v130
	s_add_i32 s0, s16, s38
	v_or_b32_e32 v146, s0, v1
	v_ashrrev_i32_e32 v147, 31, v146
	v_lshl_add_u64 v[212:213], s[18:19], 0, v[214:215]
	v_lshlrev_b64 v[148:149], 12, v[146:147]
	v_addc_co_u32_e32 v131, vcc, 0, v131, vcc
	v_lshl_add_u64 v[148:149], v[212:213], 0, v[148:149]
	s_barrier
	global_load_dwordx4 v[138:141], v[132:133], off offset:64
	global_load_dwordx4 v[134:137], v[132:133], off offset:512
	global_load_dwordx4 v[142:145], v[130:131], off
	s_nop 0
	global_load_dwordx4 v[130:133], v[132:133], off offset:576
	s_nop 0
	global_load_dwordx4 v[206:209], v[148:149], off nt
	global_load_dwordx4 v[202:205], v[148:149], off offset:64 nt
	global_load_dwordx4 v[198:201], v[148:149], off offset:512 nt
	global_load_dwordx4 v[194:197], v[148:149], off offset:576 nt
	v_or_b32_e32 v148, 16, v146
	v_ashrrev_i32_e32 v149, 31, v148
	v_lshlrev_b64 v[148:149], 12, v[148:149]
	v_lshl_add_u64 v[148:149], v[212:213], 0, v[148:149]
	global_load_dwordx4 v[190:193], v[148:149], off nt
	global_load_dwordx4 v[186:189], v[148:149], off offset:64 nt
	global_load_dwordx4 v[182:185], v[148:149], off offset:512 nt
	global_load_dwordx4 v[178:181], v[148:149], off offset:576 nt
	v_or_b32_e32 v148, 32, v146
	v_or_b32_e32 v146, 48, v146
	v_ashrrev_i32_e32 v149, 31, v148
	v_ashrrev_i32_e32 v147, 31, v146
	v_lshlrev_b64 v[148:149], 12, v[148:149]
	v_lshlrev_b64 v[146:147], 12, v[146:147]
	v_lshl_add_u64 v[148:149], v[212:213], 0, v[148:149]
	v_lshl_add_u64 v[146:147], v[212:213], 0, v[146:147]
	global_load_dwordx4 v[174:177], v[148:149], off nt
	global_load_dwordx4 v[170:173], v[148:149], off offset:64 nt
	global_load_dwordx4 v[166:169], v[148:149], off offset:512 nt
	global_load_dwordx4 v[162:165], v[148:149], off offset:576 nt
	global_load_dwordx4 v[158:161], v[146:147], off nt
	global_load_dwordx4 v[154:157], v[146:147], off offset:64 nt
	global_load_dwordx4 v[150:153], v[146:147], off offset:512 nt
	s_nop 0
	global_load_dwordx4 v[146:149], v[146:147], off offset:576 nt
	v_mbcnt_lo_u32_b32 v216, -1, 0
	v_mbcnt_hi_u32_b32 v217, -1, v216
	v_and_b32_e32 v220, 64, v217
	v_add_u32_e32 v228, 64, v220
	v_mov_b32_e32 v220, v127
	v_mov_b32_e32 v221, v128
	v_mov_b32_e32 v222, v126
	v_mov_b32_e32 v223, v129
	v_pk_add_f32 v[220:221], v[220:221], v[222:223]
	v_mov_b32_e32 v222, v123
	v_mov_b32_e32 v223, v124
	v_mov_b32_e32 v224, v122
	v_mov_b32_e32 v225, v125
	v_pk_add_f32 v[222:223], v[222:223], v[224:225]
	v_add_f32_e32 v220, v220, v221
	v_pk_add_f32 v[222:223], v[222:223], v[222:223] op_sel_hi:[0,1]
	v_xor_b32_e32 v216, 16, v217
	v_add_f32_e32 v221, 0, v220
	v_add_f32_e32 v225, v118, v119
	v_add_f32_e32 v227, v120, v121
	v_mov_b32_e32 v224, v110
	v_mov_b32_e32 v226, v111
	v_mov_b32_e32 v222, v112
	v_mov_b32_e32 v220, v113
	v_cmp_lt_i32_e32 vcc, v216, v228
	v_pk_add_f32 v[224:225], v[224:225], v[226:227]
	v_pk_add_f32 v[220:221], v[222:223], v[220:221]
	v_cndmask_b32_e32 v216, v217, v216, vcc
	v_pk_add_f32 v[220:221], v[224:225], v[220:221]
	v_lshlrev_b32_e32 v216, 2, v216
	v_add_f32_e32 v221, v220, v221
	ds_bpermute_b32 v222, v216, v221
	v_xor_b32_e32 v220, 32, v217
	v_cmp_lt_i32_e32 vcc, v220, v228
	v_mov_b32_e32 v224, v127
	v_mov_b32_e32 v223, v126
	v_cndmask_b32_e32 v217, v217, v220, vcc
	v_lshlrev_b32_e32 v220, 2, v217
	s_waitcnt lgkmcnt(0)
	v_add_f32_e32 v217, v221, v222
	ds_bpermute_b32 v221, v220, v217
	v_mov_b32_e32 v225, v123
	s_lshl_b32 s0, s34, 3
	s_add_i32 s2, s0, 0
	s_waitcnt lgkmcnt(0)
	v_add_f32_e32 v221, v217, v221
	v_fmamk_f32 v222, v221, 0xbc800000, v129
	v_fmac_f32_e32 v224, 0xbc800000, v221
	v_fmamk_f32 v217, v221, 0xbc800000, v128
	v_fmac_f32_e32 v223, 0xbc800000, v221
	v_mul_f32_e32 v224, v224, v224
	v_mul_f32_e32 v222, v222, v222
	v_fmac_f32_e32 v224, v223, v223
	v_fmac_f32_e32 v222, v217, v217
	v_add_f32_e32 v217, v224, v222
	v_fmamk_f32 v223, v221, 0xbc800000, v125
	v_mov_b32_e32 v224, v122
	v_fmac_f32_e32 v225, 0xbc800000, v221
	v_fmamk_f32 v222, v221, 0xbc800000, v124
	v_fmac_f32_e32 v224, 0xbc800000, v221
	v_mul_f32_e32 v225, v225, v225
	v_mul_f32_e32 v223, v223, v223
	v_fmac_f32_e32 v225, v224, v224
	v_fmac_f32_e32 v223, v222, v222
	v_add_f32_e32 v222, v225, v223
	v_mov_b32_e32 v225, v119
	v_fmamk_f32 v223, v221, 0xbc800000, v121
	v_mov_b32_e32 v224, v118
	v_fmac_f32_e32 v225, 0xbc800000, v221
	v_add_f32_e32 v217, v217, v222
	v_fmamk_f32 v222, v221, 0xbc800000, v120
	v_fmac_f32_e32 v224, 0xbc800000, v221
	v_mul_f32_e32 v225, v225, v225
	v_mul_f32_e32 v223, v223, v223
	v_fmac_f32_e32 v225, v224, v224
	v_fmac_f32_e32 v223, v222, v222
	v_add_f32_e32 v222, v225, v223
	v_mov_b32_e32 v225, v111
	v_fmamk_f32 v223, v221, 0xbc800000, v113
	v_mov_b32_e32 v224, v110
	v_fmac_f32_e32 v225, 0xbc800000, v221
	v_add_f32_e32 v217, v222, v217
	v_fmamk_f32 v222, v221, 0xbc800000, v112
	v_fmac_f32_e32 v224, 0xbc800000, v221
	v_mul_f32_e32 v225, v225, v225
	v_mul_f32_e32 v223, v223, v223
	v_fmac_f32_e32 v225, v224, v224
	v_fmac_f32_e32 v223, v222, v222
	v_add_f32_e32 v222, v225, v223
	v_add_f32_e32 v217, v222, v217
	ds_bpermute_b32 v222, v216, v217
	s_waitcnt lgkmcnt(0)
	v_add_f32_e32 v222, v217, v222
	ds_bpermute_b32 v223, v220, v222
	v_and_b32_e32 v217, 63, v0
	v_cmp_gt_u32_e32 vcc, 16, v217
	s_and_saveexec_b64 s[0:1], vcc
	s_cbranch_execz .LBB0_1266
	s_lshl_b32 s4, s13, 11
	s_add_i32 s4, s2, s4
	v_mul_f32_e32 v224, 0x3c800000, v221
	v_lshl_add_u32 v221, v1, 5, s4
	s_waitcnt lgkmcnt(0)
	v_add_f32_e32 v225, v222, v223
	ds_write_b64 v221, v[224:225]

;     __device__ __forceinline__ void fused(f32x4 (&acc)[2][2][4][2], const Unit& u, int wr, int wc, int fr, int fq, PG8_LAS unsigned char* lds, int wid, int lane) const {
;     ...
; #pragma unroll
;         for (int ai = 0; ai < 2; ++ai)
; #pragma unroll
;             for (int m = 0; m < 4; ++m) { const int r = ai * HALF + wr * 64 + m * 16 + fr; const f32x2v sr = S[r]; const size_t off = (size_t)(u.pm * BM + r) * ldc + col0;
; #pragma unroll
;                 for (int bj = 0; bj < 2; ++bj)
; #pragma unroll
;                     for (int n = 0; n < 2; ++n) { const f32x4 bs = ai == 0 ? pre[m][bj][n] : *(const f32x4*)(base + off + bj * HALF + n * 16); f32x4 o = bs + cvv[bj][n] * (acc[ai][bj][m][n] * sr.y);
;                         if (bad) o = (f32x4){qnan, qnan, qnan, qnan}; *(f32x4*)(out + off + bj * HALF + n * 16) = o; }
.LBB0_1304:
	s_or_b64 exec, exec, s[2:3]
	v_lshl_add_u32 v0, v219, 3, 0
	s_waitcnt lgkmcnt(0)
	s_barrier
	v_add_u32_e32 v216, 0x2000, v0
	ds_read2_b64 v[220:223], v216 offset1:16
	s_waitcnt vmcnt(0) lgkmcnt(0)
	v_or_b32_e32 v217, v217, v218
	v_add_u32_e32 v0, s16, v219
	v_ashrrev_i32_e32 v1, 31, v0
	v_cmp_ne_u32_e32 vcc, 0, v217
	v_pk_mul_f32 v[128:129], v[128:129], v[220:221] op_sel:[0,1]
	v_pk_mul_f32 v[126:127], v[126:127], v[220:221] op_sel:[0,1]
	v_pk_fma_f32 v[128:129], v[144:145], v[128:129], v[208:209]
	v_pk_fma_f32 v[206:207], v[142:143], v[126:127], v[206:207]
	v_mov_b32_e32 v126, 0x7fc00000
	v_cndmask_b32_e32 v209, v129, v126, vcc
	v_cndmask_b32_e32 v208, v128, v126, vcc
	v_lshlrev_b64 v[128:129], 12, v[0:1]
	v_pk_mul_f32 v[120:121], v[120:121], v[220:221] op_sel:[0,1]
	v_pk_mul_f32 v[118:119], v[118:119], v[220:221] op_sel:[0,1]
	v_pk_mul_f32 v[112:113], v[112:113], v[220:221] op_sel:[0,1]
	v_pk_mul_f32 v[110:111], v[110:111], v[220:221] op_sel:[0,1]
	v_lshl_add_u64 v[128:129], s[76:77], 0, v[128:129]
	v_pk_fma_f32 v[118:119], v[134:135], v[118:119], v[198:199]
	v_pk_fma_f32 v[120:121], v[136:137], v[120:121], v[200:201]
	v_pk_fma_f32 v[110:111], v[130:131], v[110:111], v[194:195]
	v_pk_fma_f32 v[112:113], v[132:133], v[112:113], v[196:197]
	v_lshl_add_u64 v[128:129], v[128:129], 0, v[214:215]
	v_cndmask_b32_e32 v121, v121, v126, vcc
	v_cndmask_b32_e32 v120, v120, v126, vcc
	v_cndmask_b32_e32 v119, v119, v126, vcc
	v_cndmask_b32_e32 v118, v118, v126, vcc
	v_cndmask_b32_e32 v113, v113, v126, vcc
	v_cndmask_b32_e32 v112, v112, v126, vcc
	v_cndmask_b32_e32 v111, v111, v126, vcc
	v_cndmask_b32_e32 v110, v110, v126, vcc
	global_store_dwordx4 v[128:129], v[118:121], off offset:512 sc1
	global_store_dwordx4 v[128:129], v[110:113], off offset:576 sc1
	v_pk_mul_f32 v[124:125], v[124:125], v[220:221] op_sel:[0,1]
	v_add_u32_e32 v118, 16, v0
	v_pk_mul_f32 v[110:111], v[116:117], v[222:223] op_sel:[0,1]
	v_pk_mul_f32 v[112:113], v[114:115], v[222:223] op_sel:[0,1]
	v_ashrrev_i32_e32 v119, 31, v118
	v_pk_fma_f32 v[114:115], v[142:143], v[112:113], v[190:191]
	v_pk_fma_f32 v[110:111], v[144:145], v[110:111], v[192:193]
	v_pk_mul_f32 v[122:123], v[122:123], v[220:221] op_sel:[0,1]
	v_cndmask_b32_e32 v113, v111, v126, vcc
	v_cndmask_b32_e32 v112, v110, v126, vcc
	v_cndmask_b32_e32 v111, v115, v126, vcc
	v_cndmask_b32_e32 v110, v114, v126, vcc
	v_lshlrev_b64 v[114:115], 12, v[118:119]
	v_pk_mul_f32 v[108:109], v[108:109], v[222:223] op_sel:[0,1]
	v_pk_mul_f32 v[106:107], v[106:107], v[222:223] op_sel:[0,1]
	v_pk_mul_f32 v[104:105], v[104:105], v[222:223] op_sel:[0,1]
	v_pk_mul_f32 v[102:103], v[102:103], v[222:223] op_sel:[0,1]
	v_pk_mul_f32 v[96:97], v[96:97], v[222:223] op_sel:[0,1]
	v_pk_mul_f32 v[94:95], v[94:95], v[222:223] op_sel:[0,1]
	v_pk_fma_f32 v[122:123], v[138:139], v[122:123], v[202:203]
	v_pk_fma_f32 v[124:125], v[140:141], v[124:125], v[204:205]
	v_lshl_add_u64 v[114:115], s[76:77], 0, v[114:115]
	v_pk_fma_f32 v[106:107], v[138:139], v[106:107], v[186:187]
	v_pk_fma_f32 v[108:109], v[140:141], v[108:109], v[188:189]
	v_pk_fma_f32 v[102:103], v[134:135], v[102:103], v[182:183]
	v_pk_fma_f32 v[104:105], v[136:137], v[104:105], v[184:185]
	v_pk_fma_f32 v[94:95], v[130:131], v[94:95], v[178:179]
	v_pk_fma_f32 v[96:97], v[132:133], v[96:97], v[180:181]
	v_cndmask_b32_e32 v207, v207, v126, vcc
	v_cndmask_b32_e32 v206, v206, v126, vcc
	v_cndmask_b32_e32 v125, v125, v126, vcc
	v_cndmask_b32_e32 v124, v124, v126, vcc
	v_cndmask_b32_e32 v123, v123, v126, vcc
	v_cndmask_b32_e32 v122, v122, v126, vcc
	v_lshl_add_u64 v[114:115], v[114:115], 0, v[214:215]
	v_cndmask_b32_e32 v109, v109, v126, vcc
	v_cndmask_b32_e32 v108, v108, v126, vcc
	v_cndmask_b32_e32 v107, v107, v126, vcc
	v_cndmask_b32_e32 v106, v106, v126, vcc
	v_cndmask_b32_e32 v105, v105, v126, vcc
	v_cndmask_b32_e32 v104, v104, v126, vcc
	v_cndmask_b32_e32 v103, v103, v126, vcc
	v_cndmask_b32_e32 v102, v102, v126, vcc
	v_cndmask_b32_e32 v97, v97, v126, vcc
	v_cndmask_b32_e32 v96, v96, v126, vcc
	v_cndmask_b32_e32 v95, v95, v126, vcc
	v_cndmask_b32_e32 v94, v94, v126, vcc
	global_store_dwordx4 v[128:129], v[206:209], off sc1
	global_store_dwordx4 v[128:129], v[122:125], off offset:64 sc1
	global_store_dwordx4 v[114:115], v[110:113], off sc1
	global_store_dwordx4 v[114:115], v[106:109], off offset:64 sc1
	global_store_dwordx4 v[114:115], v[102:105], off offset:512 sc1
	global_store_dwordx4 v[114:115], v[94:97], off offset:576 sc1
	ds_read2_b64 v[94:97], v216 offset0:32 offset1:48
	v_add_u32_e32 v102, 32, v0
	v_ashrrev_i32_e32 v103, 31, v102
	v_lshlrev_b64 v[102:103], 12, v[102:103]
	v_lshl_add_u64 v[102:103], s[76:77], 0, v[102:103]
	s_waitcnt lgkmcnt(0)
;     __device__ __forceinline__ void fused(f32x4 (&acc)[2][2][4][2], const Unit& u, int wr, int wc, int fr, int fq, PG8_LAS unsigned char* lds, int wid, int lane) const {
;     ...
;             for (int m = 0; m < 4; ++m) { const int r = ai * HALF + wr * 64 + m * 16 + fr; const f32x2v sr = S[r]; const size_t off = (size_t)(u.pm * BM + r) * ldc + col0;
; #pragma unroll
;                 for (int bj = 0; bj < 2; ++bj)
; #pragma unroll
;                     for (int n = 0; n < 2; ++n) { const f32x4 bs = ai == 0 ? pre[m][bj][n] : *(const f32x4*)(base + off + bj * HALF + n * 16); f32x4 o = bs + cvv[bj][n] * (acc[ai][bj][m][n] * sr.y);
;                         if (bad) o = (f32x4){qnan, qnan, qnan, qnan}; *(f32x4*)(out + off + bj * HALF + n * 16) = o; }
	v_pk_mul_f32 v[88:89], v[88:89], v[94:95] op_sel:[0,1]
	v_pk_mul_f32 v[86:87], v[86:87], v[94:95] op_sel:[0,1]
	v_pk_mul_f32 v[80:81], v[80:81], v[94:95] op_sel:[0,1]
	v_pk_mul_f32 v[78:79], v[78:79], v[94:95] op_sel:[0,1]
	v_pk_fma_f32 v[86:87], v[134:135], v[86:87], v[166:167]
	v_pk_fma_f32 v[88:89], v[136:137], v[88:89], v[168:169]
	v_pk_fma_f32 v[78:79], v[130:131], v[78:79], v[162:163]
	v_pk_fma_f32 v[80:81], v[132:133], v[80:81], v[164:165]
	v_lshl_add_u64 v[102:103], v[102:103], 0, v[214:215]
	v_cndmask_b32_e32 v89, v89, v126, vcc
	v_cndmask_b32_e32 v88, v88, v126, vcc
	v_cndmask_b32_e32 v87, v87, v126, vcc
	v_cndmask_b32_e32 v86, v86, v126, vcc
	v_cndmask_b32_e32 v81, v81, v126, vcc
	v_cndmask_b32_e32 v80, v80, v126, vcc
	v_cndmask_b32_e32 v79, v79, v126, vcc
	v_cndmask_b32_e32 v78, v78, v126, vcc
	global_store_dwordx4 v[102:103], v[86:89], off offset:512 sc1
	global_store_dwordx4 v[102:103], v[78:81], off offset:576 sc1
	v_pk_mul_f32 v[76:77], v[76:77], v[96:97] op_sel:[0,1]
	v_add_u32_e32 v86, 48, v0
	v_pk_mul_f32 v[78:79], v[84:85], v[96:97] op_sel:[0,1]
	v_pk_mul_f32 v[80:81], v[82:83], v[96:97] op_sel:[0,1]
	v_ashrrev_i32_e32 v87, 31, v86
	v_pk_fma_f32 v[82:83], v[142:143], v[80:81], v[158:159]
	v_pk_fma_f32 v[78:79], v[144:145], v[78:79], v[160:161]
	v_pk_mul_f32 v[74:75], v[74:75], v[96:97] op_sel:[0,1]
	v_cndmask_b32_e32 v81, v79, v126, vcc
	v_cndmask_b32_e32 v80, v78, v126, vcc
	v_cndmask_b32_e32 v79, v83, v126, vcc
	v_cndmask_b32_e32 v78, v82, v126, vcc
	v_lshlrev_b64 v[82:83], 12, v[86:87]
	v_lshl_add_u64 v[82:83], s[76:77], 0, v[82:83]
	v_pk_fma_f32 v[74:75], v[138:139], v[74:75], v[154:155]
	v_pk_fma_f32 v[76:77], v[140:141], v[76:77], v[156:157]
	v_pk_mul_f32 v[100:101], v[100:101], v[94:95] op_sel:[0,1]
	v_pk_mul_f32 v[98:99], v[98:99], v[94:95] op_sel:[0,1]
	v_pk_mul_f32 v[92:93], v[92:93], v[94:95] op_sel:[0,1]
	v_pk_mul_f32 v[90:91], v[90:91], v[94:95] op_sel:[0,1]
	v_lshl_add_u64 v[82:83], v[82:83], 0, v[214:215]
	v_cndmask_b32_e32 v77, v77, v126, vcc
	v_cndmask_b32_e32 v76, v76, v126, vcc
	v_cndmask_b32_e32 v75, v75, v126, vcc
	v_cndmask_b32_e32 v74, v74, v126, vcc
	v_pk_mul_f32 v[72:73], v[72:73], v[96:97] op_sel:[0,1]
	v_pk_mul_f32 v[70:71], v[70:71], v[96:97] op_sel:[0,1]
	v_pk_mul_f32 v[68:69], v[68:69], v[96:97] op_sel:[0,1]
	v_pk_mul_f32 v[66:67], v[66:67], v[96:97] op_sel:[0,1]
	v_pk_fma_f32 v[98:99], v[142:143], v[98:99], v[174:175]
	v_pk_fma_f32 v[100:101], v[144:145], v[100:101], v[176:177]
	v_pk_fma_f32 v[90:91], v[138:139], v[90:91], v[170:171]
	v_pk_fma_f32 v[92:93], v[140:141], v[92:93], v[172:173]
	global_store_dwordx4 v[82:83], v[74:77], off offset:64 sc1
	v_pk_fma_f32 v[70:71], v[134:135], v[70:71], v[150:151]
	v_pk_fma_f32 v[72:73], v[136:137], v[72:73], v[152:153]
	v_pk_fma_f32 v[66:67], v[130:131], v[66:67], v[146:147]
	v_pk_fma_f32 v[68:69], v[132:133], v[68:69], v[148:149]
	v_add_u32_e32 v74, 0x80, v0
	v_cndmask_b32_e32 v101, v101, v126, vcc
	v_cndmask_b32_e32 v100, v100, v126, vcc
	v_cndmask_b32_e32 v99, v99, v126, vcc
	v_cndmask_b32_e32 v98, v98, v126, vcc
	v_cndmask_b32_e32 v93, v93, v126, vcc
	v_cndmask_b32_e32 v92, v92, v126, vcc
	v_cndmask_b32_e32 v91, v91, v126, vcc
	v_cndmask_b32_e32 v90, v90, v126, vcc
	v_cndmask_b32_e32 v73, v73, v126, vcc
	v_cndmask_b32_e32 v72, v72, v126, vcc
	v_cndmask_b32_e32 v71, v71, v126, vcc
	v_cndmask_b32_e32 v70, v70, v126, vcc
	v_cndmask_b32_e32 v69, v69, v126, vcc
	v_cndmask_b32_e32 v68, v68, v126, vcc
	v_cndmask_b32_e32 v67, v67, v126, vcc
	v_cndmask_b32_e32 v66, v66, v126, vcc
	v_ashrrev_i32_e32 v75, 31, v74
	global_store_dwordx4 v[102:103], v[98:101], off sc1
	global_store_dwordx4 v[102:103], v[90:93], off offset:64 sc1
	global_store_dwordx4 v[82:83], v[78:81], off sc1
	global_store_dwordx4 v[82:83], v[70:73], off offset:512 sc1
	global_store_dwordx4 v[82:83], v[66:69], off offset:576 sc1
	ds_read2_b64 v[88:91], v216 offset0:128 offset1:144
	ds_read2_b64 v[92:95], v216 offset0:160 offset1:176
	v_mov_b32_e32 v86, 0x10000
	v_mov_b32_e32 v87, 0
	v_add_u32_e32 v66, 0x80, v0
	v_ashrrev_i32_e32 v67, 31, v66
	v_lshlrev_b64 v[68:69], 12, v[66:67]
	v_lshl_add_u64 v[70:71], v[212:213], 0, v[68:69]
	v_lshl_add_u64 v[72:73], s[76:77], 0, v[68:69]
	v_lshl_add_u64 v[72:73], v[72:73], 0, v[214:215]
	global_load_dwordx4 v[146:149], v[70:71], off nt
	global_load_dwordx4 v[150:153], v[70:71], off offset:64 nt
	global_load_dwordx4 v[154:157], v[70:71], off offset:512 nt
	global_load_dwordx4 v[158:161], v[70:71], off offset:576 nt
	v_lshl_add_u64 v[74:75], v[70:71], 0, v[86:87]
	v_lshl_add_u64 v[76:77], v[72:73], 0, v[86:87]
	global_load_dwordx4 v[162:165], v[74:75], off nt
	global_load_dwordx4 v[166:169], v[74:75], off offset:64 nt
	global_load_dwordx4 v[170:173], v[74:75], off offset:512 nt
	global_load_dwordx4 v[174:177], v[74:75], off offset:576 nt
	v_lshl_add_u64 v[78:79], v[74:75], 0, v[86:87]
	v_lshl_add_u64 v[80:81], v[76:77], 0, v[86:87]
	global_load_dwordx4 v[178:181], v[78:79], off nt
	global_load_dwordx4 v[182:185], v[78:79], off offset:64 nt
	global_load_dwordx4 v[186:189], v[78:79], off offset:512 nt
	global_load_dwordx4 v[190:193], v[78:79], off offset:576 nt
	v_lshl_add_u64 v[82:83], v[78:79], 0, v[86:87]
	v_lshl_add_u64 v[84:85], v[80:81], 0, v[86:87]
	global_load_dwordx4 v[194:197], v[82:83], off nt
	global_load_dwordx4 v[198:201], v[82:83], off offset:64 nt
	global_load_dwordx4 v[202:205], v[82:83], off offset:512 nt
	global_load_dwordx4 v[206:209], v[82:83], off offset:576 nt
	s_waitcnt lgkmcnt(0)
;     __device__ __forceinline__ void fused(f32x4 (&acc)[2][2][4][2], const Unit& u, int wr, int wc, int fr, int fq, PG8_LAS unsigned char* lds, int wid, int lane) const {
;     ...
;             for (int m = 0; m < 4; ++m) { const int r = ai * HALF + wr * 64 + m * 16 + fr; const f32x2v sr = S[r]; const size_t off = (size_t)(u.pm * BM + r) * ldc + col0;
; #pragma unroll
;                 for (int bj = 0; bj < 2; ++bj)
; #pragma unroll
;                     for (int n = 0; n < 2; ++n) { const f32x4 bs = ai == 0 ? pre[m][bj][n] : *(const f32x4*)(base + off + bj * HALF + n * 16); f32x4 o = bs + cvv[bj][n] * (acc[ai][bj][m][n] * sr.y);
;                         if (bad) o = (f32x4){qnan, qnan, qnan, qnan}; *(f32x4*)(out + off + bj * HALF + n * 16) = o; }
	v_pk_mul_f32 v[62:63], v[62:63], v[88:89] op_sel:[0,1]
	v_pk_mul_f32 v[64:65], v[64:65], v[88:89] op_sel:[0,1]
	v_pk_mul_f32 v[58:59], v[58:59], v[88:89] op_sel:[0,1]
	v_pk_mul_f32 v[60:61], v[60:61], v[88:89] op_sel:[0,1]
	v_pk_mul_f32 v[54:55], v[54:55], v[88:89] op_sel:[0,1]
	v_pk_mul_f32 v[56:57], v[56:57], v[88:89] op_sel:[0,1]
	v_pk_mul_f32 v[46:47], v[46:47], v[88:89] op_sel:[0,1]
	v_pk_mul_f32 v[48:49], v[48:49], v[88:89] op_sel:[0,1]
	s_waitcnt vmcnt(15)
	v_pk_fma_f32 v[62:63], v[142:143], v[62:63], v[146:147]
	v_pk_fma_f32 v[64:65], v[144:145], v[64:65], v[148:149]
	v_cndmask_b32_e32 v62, v62, v126, vcc
	v_cndmask_b32_e32 v63, v63, v126, vcc
	v_cndmask_b32_e32 v64, v64, v126, vcc
	v_cndmask_b32_e32 v65, v65, v126, vcc
	global_store_dwordx4 v[72:73], v[62:65], off sc1
	s_waitcnt vmcnt(15)
	v_pk_fma_f32 v[58:59], v[138:139], v[58:59], v[150:151]
	v_pk_fma_f32 v[60:61], v[140:141], v[60:61], v[152:153]
	v_cndmask_b32_e32 v58, v58, v126, vcc
	v_cndmask_b32_e32 v59, v59, v126, vcc
	v_cndmask_b32_e32 v60, v60, v126, vcc
	v_cndmask_b32_e32 v61, v61, v126, vcc
	global_store_dwordx4 v[72:73], v[58:61], off offset:64 sc1
	s_waitcnt vmcnt(15)
	v_pk_fma_f32 v[54:55], v[134:135], v[54:55], v[154:155]
	v_pk_fma_f32 v[56:57], v[136:137], v[56:57], v[156:157]
	v_cndmask_b32_e32 v54, v54, v126, vcc
	v_cndmask_b32_e32 v55, v55, v126, vcc
	v_cndmask_b32_e32 v56, v56, v126, vcc
	v_cndmask_b32_e32 v57, v57, v126, vcc
	global_store_dwordx4 v[72:73], v[54:57], off offset:512 sc1
	s_waitcnt vmcnt(15)
	v_pk_fma_f32 v[46:47], v[130:131], v[46:47], v[158:159]
	v_pk_fma_f32 v[48:49], v[132:133], v[48:49], v[160:161]
	v_cndmask_b32_e32 v46, v46, v126, vcc
	v_cndmask_b32_e32 v47, v47, v126, vcc
	v_cndmask_b32_e32 v48, v48, v126, vcc
	v_cndmask_b32_e32 v49, v49, v126, vcc
	global_store_dwordx4 v[72:73], v[46:49], off offset:576 sc1
	v_pk_mul_f32 v[50:51], v[50:51], v[90:91] op_sel:[0,1]
	v_pk_mul_f32 v[52:53], v[52:53], v[90:91] op_sel:[0,1]
	v_pk_mul_f32 v[42:43], v[42:43], v[90:91] op_sel:[0,1]
	v_pk_mul_f32 v[44:45], v[44:45], v[90:91] op_sel:[0,1]
	v_pk_mul_f32 v[38:39], v[38:39], v[90:91] op_sel:[0,1]
	v_pk_mul_f32 v[40:41], v[40:41], v[90:91] op_sel:[0,1]
	v_pk_mul_f32 v[30:31], v[30:31], v[90:91] op_sel:[0,1]
	v_pk_mul_f32 v[32:33], v[32:33], v[90:91] op_sel:[0,1]
	s_waitcnt vmcnt(15)
	v_pk_fma_f32 v[50:51], v[142:143], v[50:51], v[162:163]
	v_pk_fma_f32 v[52:53], v[144:145], v[52:53], v[164:165]
	v_cndmask_b32_e32 v50, v50, v126, vcc
	v_cndmask_b32_e32 v51, v51, v126, vcc
	v_cndmask_b32_e32 v52, v52, v126, vcc
	v_cndmask_b32_e32 v53, v53, v126, vcc
	global_store_dwordx4 v[76:77], v[50:53], off sc1
	s_waitcnt vmcnt(15)
	v_pk_fma_f32 v[42:43], v[138:139], v[42:43], v[166:167]
	v_pk_fma_f32 v[44:45], v[140:141], v[44:45], v[168:169]
	v_cndmask_b32_e32 v42, v42, v126, vcc
	v_cndmask_b32_e32 v43, v43, v126, vcc
	v_cndmask_b32_e32 v44, v44, v126, vcc
	v_cndmask_b32_e32 v45, v45, v126, vcc
	global_store_dwordx4 v[76:77], v[42:45], off offset:64 sc1
	s_waitcnt vmcnt(15)
	v_pk_fma_f32 v[38:39], v[134:135], v[38:39], v[170:171]
	v_pk_fma_f32 v[40:41], v[136:137], v[40:41], v[172:173]
	v_cndmask_b32_e32 v38, v38, v126, vcc
	v_cndmask_b32_e32 v39, v39, v126, vcc
	v_cndmask_b32_e32 v40, v40, v126, vcc
	v_cndmask_b32_e32 v41, v41, v126, vcc
	global_store_dwordx4 v[76:77], v[38:41], off offset:512 sc1
	s_waitcnt vmcnt(15)
;     __device__ __forceinline__ void fused(f32x4 (&acc)[2][2][4][2], const Unit& u, int wr, int wc, int fr, int fq, PG8_LAS unsigned char* lds, int wid, int lane) const {
;     ...
;             for (int m = 0; m < 4; ++m) { const int r = ai * HALF + wr * 64 + m * 16 + fr; const f32x2v sr = S[r]; const size_t off = (size_t)(u.pm * BM + r) * ldc + col0;
; #pragma unroll
;                 for (int bj = 0; bj < 2; ++bj)
; #pragma unroll
;                     for (int n = 0; n < 2; ++n) { const f32x4 bs = ai == 0 ? pre[m][bj][n] : *(const f32x4*)(base + off + bj * HALF + n * 16); f32x4 o = bs + cvv[bj][n] * (acc[ai][bj][m][n] * sr.y);
;                         if (bad) o = (f32x4){qnan, qnan, qnan, qnan}; *(f32x4*)(out + off + bj * HALF + n * 16) = o; }
	v_pk_fma_f32 v[30:31], v[130:131], v[30:31], v[174:175]
	v_pk_fma_f32 v[32:33], v[132:133], v[32:33], v[176:177]
	v_cndmask_b32_e32 v30, v30, v126, vcc
	v_cndmask_b32_e32 v31, v31, v126, vcc
	v_cndmask_b32_e32 v32, v32, v126, vcc
	v_cndmask_b32_e32 v33, v33, v126, vcc
	global_store_dwordx4 v[76:77], v[30:33], off offset:576 sc1
	v_pk_mul_f32 v[34:35], v[34:35], v[92:93] op_sel:[0,1]
	v_pk_mul_f32 v[36:37], v[36:37], v[92:93] op_sel:[0,1]
	v_pk_mul_f32 v[26:27], v[26:27], v[92:93] op_sel:[0,1]
	v_pk_mul_f32 v[28:29], v[28:29], v[92:93] op_sel:[0,1]
	v_pk_mul_f32 v[22:23], v[22:23], v[92:93] op_sel:[0,1]
	v_pk_mul_f32 v[24:25], v[24:25], v[92:93] op_sel:[0,1]
	v_pk_mul_f32 v[14:15], v[14:15], v[92:93] op_sel:[0,1]
	v_pk_mul_f32 v[16:17], v[16:17], v[92:93] op_sel:[0,1]
	s_waitcnt vmcnt(15)
	v_pk_fma_f32 v[34:35], v[142:143], v[34:35], v[178:179]
	v_pk_fma_f32 v[36:37], v[144:145], v[36:37], v[180:181]
	v_cndmask_b32_e32 v34, v34, v126, vcc
	v_cndmask_b32_e32 v35, v35, v126, vcc
	v_cndmask_b32_e32 v36, v36, v126, vcc
	v_cndmask_b32_e32 v37, v37, v126, vcc
	global_store_dwordx4 v[80:81], v[34:37], off sc1
	s_waitcnt vmcnt(15)
	v_pk_fma_f32 v[26:27], v[138:139], v[26:27], v[182:183]
	v_pk_fma_f32 v[28:29], v[140:141], v[28:29], v[184:185]
	v_cndmask_b32_e32 v26, v26, v126, vcc
	v_cndmask_b32_e32 v27, v27, v126, vcc
	v_cndmask_b32_e32 v28, v28, v126, vcc
	v_cndmask_b32_e32 v29, v29, v126, vcc
	global_store_dwordx4 v[80:81], v[26:29], off offset:64 sc1
	s_waitcnt vmcnt(15)
	v_pk_fma_f32 v[22:23], v[134:135], v[22:23], v[186:187]
	v_pk_fma_f32 v[24:25], v[136:137], v[24:25], v[188:189]
	v_cndmask_b32_e32 v22, v22, v126, vcc
	v_cndmask_b32_e32 v23, v23, v126, vcc
	v_cndmask_b32_e32 v24, v24, v126, vcc
	v_cndmask_b32_e32 v25, v25, v126, vcc
	global_store_dwordx4 v[80:81], v[22:25], off offset:512 sc1
	s_waitcnt vmcnt(15)
	v_pk_fma_f32 v[14:15], v[130:131], v[14:15], v[190:191]
	v_pk_fma_f32 v[16:17], v[132:133], v[16:17], v[192:193]
	v_cndmask_b32_e32 v14, v14, v126, vcc
	v_cndmask_b32_e32 v15, v15, v126, vcc
	v_cndmask_b32_e32 v16, v16, v126, vcc
	v_cndmask_b32_e32 v17, v17, v126, vcc
	global_store_dwordx4 v[80:81], v[14:17], off offset:576 sc1
	v_pk_mul_f32 v[18:19], v[18:19], v[94:95] op_sel:[0,1]
	v_pk_mul_f32 v[20:21], v[20:21], v[94:95] op_sel:[0,1]
	v_pk_mul_f32 v[10:11], v[10:11], v[94:95] op_sel:[0,1]
	v_pk_mul_f32 v[12:13], v[12:13], v[94:95] op_sel:[0,1]
	v_pk_mul_f32 v[6:7], v[6:7], v[94:95] op_sel:[0,1]
	v_pk_mul_f32 v[8:9], v[8:9], v[94:95] op_sel:[0,1]
	v_pk_mul_f32 v[2:3], v[2:3], v[94:95] op_sel:[0,1]
	v_pk_mul_f32 v[4:5], v[4:5], v[94:95] op_sel:[0,1]
	s_waitcnt vmcnt(15)
	v_pk_fma_f32 v[18:19], v[142:143], v[18:19], v[194:195]
	v_pk_fma_f32 v[20:21], v[144:145], v[20:21], v[196:197]
	v_cndmask_b32_e32 v18, v18, v126, vcc
	v_cndmask_b32_e32 v19, v19, v126, vcc
	v_cndmask_b32_e32 v20, v20, v126, vcc
	v_cndmask_b32_e32 v21, v21, v126, vcc
	global_store_dwordx4 v[84:85], v[18:21], off sc1
	s_waitcnt vmcnt(15)
	v_pk_fma_f32 v[10:11], v[138:139], v[10:11], v[198:199]
	v_pk_fma_f32 v[12:13], v[140:141], v[12:13], v[200:201]
	v_cndmask_b32_e32 v10, v10, v126, vcc
	v_cndmask_b32_e32 v11, v11, v126, vcc
	v_cndmask_b32_e32 v12, v12, v126, vcc
	v_cndmask_b32_e32 v13, v13, v126, vcc
	global_store_dwordx4 v[84:85], v[10:13], off offset:64 sc1
	s_waitcnt vmcnt(15)
	v_pk_fma_f32 v[6:7], v[134:135], v[6:7], v[202:203]
	v_pk_fma_f32 v[8:9], v[136:137], v[8:9], v[204:205]
	v_cndmask_b32_e32 v6, v6, v126, vcc
	v_cndmask_b32_e32 v7, v7, v126, vcc
	v_cndmask_b32_e32 v8, v8, v126, vcc
	v_cndmask_b32_e32 v9, v9, v126, vcc
	global_store_dwordx4 v[84:85], v[6:9], off offset:512 sc1
	s_waitcnt vmcnt(15)
	v_pk_fma_f32 v[2:3], v[130:131], v[2:3], v[206:207]
	v_pk_fma_f32 v[4:5], v[132:133], v[4:5], v[208:209]
	v_cndmask_b32_e32 v2, v2, v126, vcc
	v_cndmask_b32_e32 v3, v3, v126, vcc
	v_cndmask_b32_e32 v4, v4, v126, vcc
	v_cndmask_b32_e32 v5, v5, v126, vcc
	global_store_dwordx4 v[84:85], v[2:5], off offset:576 sc1
